# speedup vs baseline: 1.0012x; 1.0012x over previous
;   const int tid = tidx, lane = tid & 63, w = tid >> 6;
;   const int wm = w >> 1, wn = w & 1;
;   const int l15 = lane & 15, quad = lane >> 4;
;   constexpr int NB = (TN * 32 * 8) / NT;
;   constexpr int BUFE = (256 + (TN > 4 ? 192 : 128)) * GSTR;
;   u32x4 ra0[4], ra1[4];
;   u32x4 rb0[NB], rb1[NB];
;   const int cr = tid >> 3, ck = tid & 7;
;   const unsigned aoffb = (unsigned)(cr * lda + ck * 8) * 2u;
;   const unsigned boffb = (unsigned)(cr * ldb + ck * 8) * 2u;
; __device__ __forceinline__ void phase_inproj(const Params& p, const int tidx) {
;     ...
;   const bool swz = (gridDim.x == 256);
;   const int xcd = blockIdx.x & 7, li = blockIdx.x >> 3;
;   for (int tile = blockIdx.x, rnd = 0; tile < 128 * NTN; tile += gridDim.x, rnd++) {
;     int mt = tile / NTN, nt = tile % NTN;
;     if (swz) {
;       int j = rnd * 32 + li;
;       int g = j / (4 * NTN), rem = j % (4 * NTN);
;       nt = rem >> 2;
;       mt = xcd * 16 + g * 4 + (rem & 3);
;     }
.LBB0_578:
	s_andn2_b64 vcc, exec, s[10:11]
	s_cbranch_vccnz .LBB0_588
	v_readlane_b32 s10, v252, 45
	v_readlane_b32 s11, v252, 46
	s_andn2_b64 vcc, exec, s[10:11]
	s_cbranch_vccnz .LBB0_588
	s_waitcnt vmcnt(14)
	v_ashrrev_i32_e32 v10, 1, v150
	s_waitcnt lgkmcnt(0)
	v_and_b32_e32 v8, 15, v150
	v_and_b32_e32 v10, 0xffffffc0, v10
	v_lshlrev_b32_e32 v0, 4, v150
	s_movk_i32 s5, 0xa0
	v_or_b32_e32 v11, v10, v8
	v_ashrrev_i32_e32 v2, 3, v150
	v_and_b32_e32 v3, 0x70, v0
	v_mul_lo_u32 v20, v11, s5
	s_add_i32 s0, 0, 0xf000
	v_lshl_or_b32 v0, v2, 11, v3
	v_add_u32_e32 v9, 0, v3
	v_mul_lo_u32 v2, v2, s5
	v_add_u32_e32 v11, s0, v20
	v_readlane_b32 s0, v254, 12
	v_and_b32_e32 v18, 48, v150
	s_waitcnt vmcnt(13)
	v_and_b32_e32 v12, 0x4f, v150
	v_add_u32_e32 v22, v9, v2
	v_mov_b32_e32 v9, s0
	v_lshrrev_b32_e32 v17, 2, v150
	v_add_u32_e32 v19, 0, v18
	v_add_u32_e32 v14, s0, v18
	v_lshrrev_b32_e32 v23, 3, v150
	v_and_b32_e32 v25, 4, v23
	v_lshlrev_b32_e32 v25, 2, v25
	v_and_or_b32 v25, v23, 35, v25
	v_and_b32_e32 v23, 24, v23
	v_lshrrev_b32_e32 v23, 1, v23
	v_or_b32_e32 v23, v25, v23
	v_mul_u32_u24_e32 v23, 0xa0, v23
	v_add_u32_e32 v23, 0xa000, v23
	v_add_u32_e32 v23, v23, v3
	s_waitcnt vmcnt(11)
	v_mad_u32_u24 v28, v12, s5, v9
	v_and_or_b32 v10, v17, 12, v10
	v_and_b32_e32 v17, 64, v150
	s_movk_i32 s0, 0x110
	v_mul_u32_u24_e32 v21, 0xa0, v12
	v_add_u32_e32 v13, 0xf000, v19
	s_waitcnt vmcnt(8)
	v_add_u32_e32 v15, 0, v20
	v_mad_u32_u24 v16, v12, s5, 0
	v_add_u32_e32 v2, 0x1400, v11
	v_add_u32_e32 v3, 0x1e00, v11
	v_add_u32_e32 v9, 0xa00, v28
	v_add_u32_e32 v11, 0x1400, v28
	v_add_u32_e32 v12, 0x1e00, v28
	v_lshl_add_u32 v17, v17, 1, 0
	v_lshlrev_b32_e32 v8, 1, v8
	v_mul_lo_u32 v10, v10, s0
	v_add_u32_e32 v24, 0x2800, v22
	v_add_u32_e32 v25, 0x2800, v23
	v_add_u32_e32 v26, 0x5000, v22
	v_add_u32_e32 v27, 0x7800, v22
	v_add3_u32 v29, v17, v8, v10
	v_cmp_gt_i32_e64 s[10:11], s36, v150
	s_mov_b32 s0, 0
	v_add_u32_e32 v30, v15, v18
	v_add_u32_e32 v31, v16, v18
	v_add_u32_e32 v32, v13, v20
	v_add_u32_e32 v33, v14, v21
	v_add_u32_e32 v34, v2, v18
	v_add_u32_e32 v35, v3, v18
	v_add_u32_e32 v36, v9, v18
	v_add_u32_e32 v37, v11, v18
	v_add_u32_e32 v38, v12, v18
	v_lshrrev_b32_e32 v170, 1, v150
	v_and_b32_e32 v171, 1, v150
	v_lshlrev_b32_e32 v170, 11, v170
	v_lshl_or_b32 v170, v171, 7, v170
	v_and_b32_e32 v171, 3, v150
	v_lshlrev_b32_e32 v171, 7, v171
	v_lshrrev_b32_e32 v172, 2, v150
	v_lshl_or_b32 v171, v172, 11, v171
	v_readlane_b32 s18, v251, 0
	s_branch .LBB0_582

;     ...
;   G_LOAD(ra0, rb0, 0);
;   G_LOAD(ra1, rb1, 64);
;   __syncthreads();
;   G_STORE(ra0, rb0, 0);
;   __syncthreads();
;   G_READ(fa0, fb0, 0, 0);
; #pragma unroll
;   for (int k0 = 0; k0 < K; k0 += 128) {
;     G_READ(fa1, fb1, 0, 32);
;     if (k0 + 128 < K) G_LOAD(ra0, rb0, k0 + 128);
;     __builtin_amdgcn_sched_barrier(0);
;     G_MFMA_ST(fa0, fb0, ra1, rb1, 1);
;     __syncthreads();
;     G_READ(fa0, fb0, 1, 0);
;     __builtin_amdgcn_sched_barrier(0);
;     G_MFMA(fa1, fb1);
; __device__ __forceinline__ void phase_inproj(const Params& p, const int tidx) {
;     ...
;   for (int tile = blockIdx.x, rnd = 0; tile < 128 * NTN; tile += gridDim.x, rnd++) {
;     int mt = tile / NTN, nt = tile % NTN;
;     if (swz) {
;       int j = rnd * 32 + li;
;       int g = j / (4 * NTN), rem = j % (4 * NTN);
;       nt = rem >> 2;
;       mt = xcd * 16 + g * 4 + (rem & 3);
;     }
;     f32x4 acc[4][4];
;     zero_acc<4>(acc);
;     gemm_main<4, 1024>(acc, H + (size_t)mt * 256 * 1024, 1024, W + (size_t)nt * 128 * 1024, 1024, sA, sB, tidx);
.LBB0_585:
	s_ashr_i32 s15, s14, 31
	s_lshl_b64 s[16:17], s[14:15], 19
	s_add_u32 s16, s50, s16
	s_addc_u32 s17, s51, s17
	v_lshl_add_u64 v[2:3], s[16:17], 0, v[0:1]
	s_mov_b32 s5, 0x20000
	s_ashr_i32 s13, s12, 31
	v_add_co_u32_e32 v8, vcc, s5, v2
	s_lshl_b64 s[20:21], s[12:13], 18
	v_readlane_b32 s22, v251, 20
	v_addc_co_u32_e32 v9, vcc, 0, v3, vcc
	s_mov_b32 s13, 0x40000
	v_readlane_b32 s23, v251, 21
	s_add_u32 s20, s22, s20
	global_load_dwordx4 v[40:43], v[2:3], off
	global_load_dwordx4 v[44:47], v[8:9], off
	v_add_co_u32_e32 v10, vcc, s13, v2
	s_addc_u32 s21, s23, s21
	s_nop 0
	v_addc_co_u32_e32 v11, vcc, 0, v3, vcc
	global_load_dwordx4 v[48:51], v[10:11], off
	v_add_co_u32_e32 v12, vcc, s35, v2
	v_lshl_add_u64 v[14:15], s[20:21], 0, v[0:1]
	s_nop 0
	v_addc_co_u32_e32 v13, vcc, 0, v3, vcc
	global_load_dwordx4 v[56:59], v[14:15], off
	global_load_dwordx4 v[52:55], v[12:13], off
	v_add_co_u32_e32 v16, vcc, s5, v14
	v_add_u32_e32 v39, v19, v20
	s_nop 0
	v_addc_co_u32_e32 v17, vcc, 0, v15, vcc
	global_load_dwordx4 v[60:63], v[16:17], off
	global_load_dwordx4 v[64:67], v[2:3], off offset:128
	global_load_dwordx4 v[68:71], v[8:9], off offset:128
	global_load_dwordx4 v[72:75], v[10:11], off offset:128
	global_load_dwordx4 v[76:79], v[14:15], off offset:128
	global_load_dwordx4 v[80:83], v[12:13], off offset:128
	global_load_dwordx4 v[84:87], v[16:17], off offset:128
	s_barrier
	s_waitcnt vmcnt(11)
	ds_write_b128 v22, v[40:43]
	s_waitcnt vmcnt(10)
	ds_write_b128 v22, v[44:47] offset:10240
	s_waitcnt vmcnt(9)
	ds_write_b128 v22, v[48:51] offset:20480
	s_waitcnt vmcnt(8)
	ds_write_b128 v23, v[56:59]
	s_waitcnt vmcnt(7)
	ds_write_b128 v22, v[52:55] offset:30720
	s_waitcnt vmcnt(6)
	ds_write_b128 v25, v[60:63]
	s_waitcnt lgkmcnt(0)
	s_barrier
	global_load_dwordx4 v[42:45], v[2:3], off offset:256
	global_load_dwordx4 v[46:49], v[8:9], off offset:256
	global_load_dwordx4 v[50:53], v[10:11], off offset:256
	global_load_dwordx4 v[54:57], v[12:13], off offset:256
	global_load_dwordx4 v[58:61], v[14:15], off offset:256
	global_load_dwordx4 v[88:91], v[16:17], off offset:256
	v_add_u32_e32 v40, v19, v21
	ds_read_b128 v[92:95], v39
	ds_read_b128 v[96:99], v39 offset:2560
	ds_read_b128 v[100:103], v39 offset:5120
	ds_read_b128 v[104:107], v39 offset:7680
	ds_read_b128 v[108:111], v40 offset:40960
	ds_read_b128 v[112:115], v40 offset:43520
	ds_read_b128 v[116:119], v40 offset:46080
	ds_read_b128 v[120:123], v40 offset:48640
	ds_read_b128 v[124:127], v30 offset:64
	ds_read_b128 v[128:131], v30 offset:2624
	ds_read_b128 v[132:135], v30 offset:5184
	ds_read_b128 v[136:139], v30 offset:7744
	ds_read_b128 v[140:143], v31 offset:41024
	ds_read_b128 v[144:147], v31 offset:43584
	ds_read_b128 v[152:155], v31 offset:46144
	ds_read_b128 v[156:159], v31 offset:48704
	s_waitcnt lgkmcnt(11)
	v_mfma_f32_16x16x32_bf16 v[174:177], v[108:111], v[92:95], 0
	s_waitcnt vmcnt(11)
	ds_write_b128 v22, v[64:67] offset:61440
	s_waitcnt vmcnt(8)
	ds_write_b128 v23, v[76:79] offset:61440
	s_waitcnt lgkmcnt(12)
	v_mfma_f32_16x16x32_bf16 v[178:181], v[112:115], v[92:95], 0
	s_waitcnt lgkmcnt(11)
	v_mfma_f32_16x16x32_bf16 v[182:185], v[116:119], v[92:95], 0
	s_waitcnt lgkmcnt(10)
	v_mfma_f32_16x16x32_bf16 v[62:65], v[120:123], v[92:95], 0
	v_mfma_f32_16x16x32_bf16 v[76:79], v[108:111], v[96:99], 0
	ds_write_b128 v24, v[68:71] offset:61440
	s_waitcnt vmcnt(6)
	ds_write_b128 v25, v[84:87] offset:61440
	v_mfma_f32_16x16x32_bf16 v[92:95], v[112:115], v[96:99], 0
	v_mfma_f32_16x16x32_bf16 v[186:189], v[116:119], v[96:99], 0
	v_mfma_f32_16x16x32_bf16 v[66:69], v[120:123], v[96:99], 0
	v_mfma_f32_16x16x32_bf16 v[84:87], v[108:111], v[100:103], 0
	ds_write_b128 v26, v[72:75] offset:61440
	v_mfma_f32_16x16x32_bf16 v[96:99], v[112:115], v[100:103], 0
	v_mfma_f32_16x16x32_bf16 v[190:193], v[116:119], v[100:103], 0
	v_mfma_f32_16x16x32_bf16 v[70:73], v[120:123], v[100:103], 0
	v_mfma_f32_16x16x32_bf16 v[100:103], v[108:111], v[104:107], 0
	ds_write_b128 v27, v[80:83] offset:61440
	v_mfma_f32_16x16x32_bf16 v[108:111], v[112:115], v[104:107], 0
	v_mfma_f32_16x16x32_bf16 v[112:115], v[116:119], v[104:107], 0
	v_mfma_f32_16x16x32_bf16 v[80:83], v[120:123], v[104:107], 0
	s_waitcnt lgkmcnt(0)
	s_barrier
	ds_read_b128 v[104:107], v39 offset:61440
	ds_read_b128 v[116:119], v39 offset:64000
	ds_read_b128 v[120:123], v32 offset:5120
	ds_read_b128 v[194:197], v32 offset:7680
	ds_read_b128 v[198:201], v33
	ds_read_b128 v[202:205], v33 offset:2560
	ds_read_b128 v[206:209], v33 offset:5120
	ds_read_b128 v[210:213], v33 offset:7680
	v_mfma_f32_16x16x32_bf16 v[174:177], v[140:143], v[124:127], v[174:177]
	v_mfma_f32_16x16x32_bf16 v[178:181], v[144:147], v[124:127], v[178:181]
	v_mfma_f32_16x16x32_bf16 v[182:185], v[152:155], v[124:127], v[182:185]
	v_mfma_f32_16x16x32_bf16 v[62:65], v[156:159], v[124:127], v[62:65]
	v_mfma_f32_16x16x32_bf16 v[74:77], v[140:143], v[128:131], v[76:79]
	v_mfma_f32_16x16x32_bf16 v[92:95], v[144:147], v[128:131], v[92:95]
	v_mfma_f32_16x16x32_bf16 v[124:127], v[152:155], v[128:131], v[186:189]
	v_mfma_f32_16x16x32_bf16 v[66:69], v[156:159], v[128:131], v[66:69]
	v_mfma_f32_16x16x32_bf16 v[84:87], v[140:143], v[132:135], v[84:87]
	v_mfma_f32_16x16x32_bf16 v[96:99], v[144:147], v[132:135], v[96:99]
	v_mfma_f32_16x16x32_bf16 v[128:131], v[152:155], v[132:135], v[190:193]
	v_mfma_f32_16x16x32_bf16 v[70:73], v[156:159], v[132:135], v[70:73]
	v_mfma_f32_16x16x32_bf16 v[100:103], v[140:143], v[136:139], v[100:103]
	v_mfma_f32_16x16x32_bf16 v[108:111], v[144:147], v[136:139], v[108:111]
	v_mfma_f32_16x16x32_bf16 v[112:115], v[152:155], v[136:139], v[112:115]
	v_mfma_f32_16x16x32_bf16 v[78:81], v[156:159], v[136:139], v[80:83]
	global_load_dwordx4 v[132:135], v[2:3], off offset:384
	global_load_dwordx4 v[136:139], v[8:9], off offset:384
	global_load_dwordx4 v[140:143], v[10:11], off offset:384
	global_load_dwordx4 v[144:147], v[12:13], off offset:384
	global_load_dwordx4 v[152:155], v[14:15], off offset:384
	global_load_dwordx4 v[156:159], v[16:17], off offset:384
	v_add_u32_e32 v41, v28, v18
	ds_read_b128 v[186:189], v30 offset:61504
	ds_read_b128 v[190:193], v30 offset:64064
	ds_read_b128 v[214:217], v34 offset:64
	ds_read_b128 v[218:221], v35 offset:64
	ds_read_b128 v[222:225], v41 offset:64
	ds_read_b128 v[226:229], v36 offset:64
	ds_read_b128 v[230:233], v37 offset:64
	ds_read_b128 v[234:237], v38 offset:64
	s_waitcnt lgkmcnt(11)
;     ...
;   for (int k0 = 0; k0 < K; k0 += 128) {
;     G_READ(fa1, fb1, 0, 32);
;     if (k0 + 128 < K) G_LOAD(ra0, rb0, k0 + 128);
;     __builtin_amdgcn_sched_barrier(0);
;     G_MFMA_ST(fa0, fb0, ra1, rb1, 1);
;     __syncthreads();
;     G_READ(fa0, fb0, 1, 0);
;     __builtin_amdgcn_sched_barrier(0);
;     G_MFMA(fa1, fb1);
;     __builtin_amdgcn_sched_barrier(0);
;     G_READ(fa1, fb1, 1, 32);
;     if (k0 + 192 < K) G_LOAD(ra1, rb1, k0 + 192);
;     __builtin_amdgcn_sched_barrier(0);
;     if (k0 + 128 < K) {
;       G_MFMA_ST(fa0, fb0, ra0, rb0, 0);
;       __syncthreads();
;       G_READ(fa0, fb0, 0, 0);
;     } else {
;       G_MFMA(fa0, fb0);
;     }
;     __builtin_amdgcn_sched_barrier(0);
;     G_MFMA(fa1, fb1);
;     __builtin_amdgcn_sched_barrier(0);
;   }
	v_mfma_f32_16x16x32_bf16 v[174:177], v[198:201], v[104:107], v[174:177]
	s_waitcnt vmcnt(11)
	ds_write_b128 v22, v[42:45]
	s_waitcnt vmcnt(7)
	ds_write_b128 v23, v[58:61]
	s_waitcnt lgkmcnt(12)
	v_mfma_f32_16x16x32_bf16 v[178:181], v[202:205], v[104:107], v[178:181]
	s_waitcnt lgkmcnt(11)
	v_mfma_f32_16x16x32_bf16 v[182:185], v[206:209], v[104:107], v[182:185]
	s_waitcnt lgkmcnt(10)
	v_mfma_f32_16x16x32_bf16 v[42:45], v[210:213], v[104:107], v[62:65]
	v_mfma_f32_16x16x32_bf16 v[58:61], v[198:201], v[116:119], v[74:77]
	ds_write_b128 v22, v[46:49] offset:10240
	s_waitcnt vmcnt(6)
	ds_write_b128 v25, v[88:91]
	v_mfma_f32_16x16x32_bf16 v[62:65], v[202:205], v[116:119], v[92:95]
	v_mfma_f32_16x16x32_bf16 v[74:77], v[206:209], v[116:119], v[124:127]
	v_mfma_f32_16x16x32_bf16 v[46:49], v[210:213], v[116:119], v[66:69]
	v_mfma_f32_16x16x32_bf16 v[66:69], v[198:201], v[120:123], v[84:87]
	ds_write_b128 v22, v[50:53] offset:20480
	v_mfma_f32_16x16x32_bf16 v[82:85], v[202:205], v[120:123], v[96:99]
	v_mfma_f32_16x16x32_bf16 v[86:89], v[206:209], v[120:123], v[128:131]
	v_mfma_f32_16x16x32_bf16 v[50:53], v[210:213], v[120:123], v[70:73]
	v_mfma_f32_16x16x32_bf16 v[70:73], v[198:201], v[194:197], v[100:103]
	ds_write_b128 v22, v[54:57] offset:30720
	v_mfma_f32_16x16x32_bf16 v[90:93], v[202:205], v[194:197], v[108:111]
	v_mfma_f32_16x16x32_bf16 v[94:97], v[206:209], v[194:197], v[112:115]
	v_mfma_f32_16x16x32_bf16 v[54:57], v[210:213], v[194:197], v[78:81]
	s_waitcnt lgkmcnt(0)
	s_barrier
	s_nop 0
	ds_read_b128 v[78:81], v39
	ds_read_b128 v[98:101], v39 offset:2560
	ds_read_b128 v[102:105], v39 offset:5120
	ds_read_b128 v[106:109], v39 offset:7680
	ds_read_b128 v[110:113], v40 offset:40960
	ds_read_b128 v[114:117], v40 offset:43520
	ds_read_b128 v[118:121], v40 offset:46080
	ds_read_b128 v[122:125], v40 offset:48640
	v_mfma_f32_16x16x32_bf16 v[126:129], v[222:225], v[186:189], v[174:177]
	v_mfma_f32_16x16x32_bf16 v[174:177], v[226:229], v[186:189], v[178:181]
	v_mfma_f32_16x16x32_bf16 v[178:181], v[230:233], v[186:189], v[182:185]
	v_mfma_f32_16x16x32_bf16 v[42:45], v[234:237], v[186:189], v[42:45]
	v_mfma_f32_16x16x32_bf16 v[58:61], v[222:225], v[190:193], v[58:61]
	v_mfma_f32_16x16x32_bf16 v[62:65], v[226:229], v[190:193], v[62:65]
	v_mfma_f32_16x16x32_bf16 v[74:77], v[230:233], v[190:193], v[74:77]
	v_mfma_f32_16x16x32_bf16 v[46:49], v[234:237], v[190:193], v[46:49]
	v_mfma_f32_16x16x32_bf16 v[66:69], v[222:225], v[214:217], v[66:69]
	v_mfma_f32_16x16x32_bf16 v[82:85], v[226:229], v[214:217], v[82:85]
	v_mfma_f32_16x16x32_bf16 v[86:89], v[230:233], v[214:217], v[86:89]
	v_mfma_f32_16x16x32_bf16 v[50:53], v[234:237], v[214:217], v[50:53]
	v_mfma_f32_16x16x32_bf16 v[70:73], v[222:225], v[218:221], v[70:73]
	v_mfma_f32_16x16x32_bf16 v[90:93], v[226:229], v[218:221], v[90:93]
	v_mfma_f32_16x16x32_bf16 v[94:97], v[230:233], v[218:221], v[94:97]
	v_mfma_f32_16x16x32_bf16 v[54:57], v[234:237], v[218:221], v[54:57]
	global_load_dwordx4 v[182:185], v[2:3], off offset:512
	global_load_dwordx4 v[186:189], v[8:9], off offset:512
	global_load_dwordx4 v[190:193], v[10:11], off offset:512
	global_load_dwordx4 v[194:197], v[12:13], off offset:512
	global_load_dwordx4 v[198:201], v[14:15], off offset:512
	global_load_dwordx4 v[202:205], v[16:17], off offset:512
	ds_read_b128 v[206:209], v30 offset:64
	ds_read_b128 v[210:213], v30 offset:2624
	ds_read_b128 v[214:217], v30 offset:5184
	ds_read_b128 v[218:221], v30 offset:7744
	ds_read_b128 v[222:225], v31 offset:41024
	ds_read_b128 v[226:229], v31 offset:43584
	ds_read_b128 v[230:233], v31 offset:46144
	ds_read_b128 v[234:237], v31 offset:48704
	s_waitcnt lgkmcnt(11)
	v_mfma_f32_16x16x32_bf16 v[126:129], v[110:113], v[78:81], v[126:129]
	s_waitcnt vmcnt(11)
	ds_write_b128 v22, v[132:135] offset:61440
	s_waitcnt vmcnt(7)
	ds_write_b128 v23, v[152:155] offset:61440
	s_waitcnt lgkmcnt(12)
	v_mfma_f32_16x16x32_bf16 v[174:177], v[114:117], v[78:81], v[174:177]
	s_waitcnt lgkmcnt(11)
	v_mfma_f32_16x16x32_bf16 v[178:181], v[118:121], v[78:81], v[178:181]
	s_waitcnt lgkmcnt(10)
	v_mfma_f32_16x16x32_bf16 v[42:45], v[122:125], v[78:81], v[42:45]
	v_mfma_f32_16x16x32_bf16 v[58:61], v[110:113], v[98:101], v[58:61]
	ds_write_b128 v24, v[136:139] offset:61440
	s_waitcnt vmcnt(6)
	ds_write_b128 v25, v[156:159] offset:61440
	v_mfma_f32_16x16x32_bf16 v[62:65], v[114:117], v[98:101], v[62:65]
	v_mfma_f32_16x16x32_bf16 v[74:77], v[118:121], v[98:101], v[74:77]
	v_mfma_f32_16x16x32_bf16 v[46:49], v[122:125], v[98:101], v[46:49]
	v_mfma_f32_16x16x32_bf16 v[66:69], v[110:113], v[102:105], v[66:69]
	ds_write_b128 v26, v[140:143] offset:61440
	v_mfma_f32_16x16x32_bf16 v[78:81], v[114:117], v[102:105], v[82:85]
	v_mfma_f32_16x16x32_bf16 v[82:85], v[118:121], v[102:105], v[86:89]
	v_mfma_f32_16x16x32_bf16 v[50:53], v[122:125], v[102:105], v[50:53]
	v_mfma_f32_16x16x32_bf16 v[70:73], v[110:113], v[106:109], v[70:73]
	ds_write_b128 v27, v[144:147] offset:61440
	v_mfma_f32_16x16x32_bf16 v[86:89], v[114:117], v[106:109], v[90:93]
	v_mfma_f32_16x16x32_bf16 v[90:93], v[118:121], v[106:109], v[94:97]
	v_mfma_f32_16x16x32_bf16 v[54:57], v[122:125], v[106:109], v[54:57]
	s_waitcnt lgkmcnt(0)
	s_barrier
;     ...
;   for (int k0 = 0; k0 < K; k0 += 128) {
;     G_READ(fa1, fb1, 0, 32);
;     if (k0 + 128 < K) G_LOAD(ra0, rb0, k0 + 128);
;     __builtin_amdgcn_sched_barrier(0);
;     G_MFMA_ST(fa0, fb0, ra1, rb1, 1);
;     __syncthreads();
;     G_READ(fa0, fb0, 1, 0);
;     __builtin_amdgcn_sched_barrier(0);
;     G_MFMA(fa1, fb1);
;     __builtin_amdgcn_sched_barrier(0);
;     G_READ(fa1, fb1, 1, 32);
;     if (k0 + 192 < K) G_LOAD(ra1, rb1, k0 + 192);
;     __builtin_amdgcn_sched_barrier(0);
;     if (k0 + 128 < K) {
;       G_MFMA_ST(fa0, fb0, ra0, rb0, 0);
;       __syncthreads();
;       G_READ(fa0, fb0, 0, 0);
;     } else {
;       G_MFMA(fa0, fb0);
;     }
;     __builtin_amdgcn_sched_barrier(0);
;     G_MFMA(fa1, fb1);
;     __builtin_amdgcn_sched_barrier(0);
;   }
	ds_read_b128 v[94:97], v39 offset:61440
	ds_read_b128 v[98:101], v39 offset:64000
	ds_read_b128 v[102:105], v32 offset:5120
	ds_read_b128 v[106:109], v32 offset:7680
	ds_read_b128 v[110:113], v33
	ds_read_b128 v[114:117], v33 offset:2560
	ds_read_b128 v[118:121], v33 offset:5120
	ds_read_b128 v[122:125], v33 offset:7680
	v_mfma_f32_16x16x32_bf16 v[126:129], v[222:225], v[206:209], v[126:129]
	v_mfma_f32_16x16x32_bf16 v[130:133], v[226:229], v[206:209], v[174:177]
	v_mfma_f32_16x16x32_bf16 v[134:137], v[230:233], v[206:209], v[178:181]
	v_mfma_f32_16x16x32_bf16 v[42:45], v[234:237], v[206:209], v[42:45]
	v_mfma_f32_16x16x32_bf16 v[58:61], v[222:225], v[210:213], v[58:61]
	v_mfma_f32_16x16x32_bf16 v[62:65], v[226:229], v[210:213], v[62:65]
	v_mfma_f32_16x16x32_bf16 v[74:77], v[230:233], v[210:213], v[74:77]
	v_mfma_f32_16x16x32_bf16 v[46:49], v[234:237], v[210:213], v[46:49]
	v_mfma_f32_16x16x32_bf16 v[66:69], v[222:225], v[214:217], v[66:69]
	v_mfma_f32_16x16x32_bf16 v[78:81], v[226:229], v[214:217], v[78:81]
	v_mfma_f32_16x16x32_bf16 v[82:85], v[230:233], v[214:217], v[82:85]
	v_mfma_f32_16x16x32_bf16 v[50:53], v[234:237], v[214:217], v[50:53]
	v_mfma_f32_16x16x32_bf16 v[70:73], v[222:225], v[218:221], v[70:73]
	v_mfma_f32_16x16x32_bf16 v[86:89], v[226:229], v[218:221], v[86:89]
	v_mfma_f32_16x16x32_bf16 v[90:93], v[230:233], v[218:221], v[90:93]
	v_mfma_f32_16x16x32_bf16 v[54:57], v[234:237], v[218:221], v[54:57]
	global_load_dwordx4 v[138:141], v[2:3], off offset:640
	global_load_dwordx4 v[142:145], v[8:9], off offset:640
	global_load_dwordx4 v[152:155], v[10:11], off offset:640
	global_load_dwordx4 v[156:159], v[12:13], off offset:640
	global_load_dwordx4 v[174:177], v[14:15], off offset:640
	global_load_dwordx4 v[178:181], v[16:17], off offset:640
	ds_read_b128 v[206:209], v30 offset:61504
	ds_read_b128 v[210:213], v30 offset:64064
	ds_read_b128 v[214:217], v34 offset:64
	ds_read_b128 v[218:221], v35 offset:64
	ds_read_b128 v[222:225], v41 offset:64
	ds_read_b128 v[226:229], v36 offset:64
	ds_read_b128 v[230:233], v37 offset:64
	ds_read_b128 v[234:237], v38 offset:64
	s_waitcnt lgkmcnt(11)
	v_mfma_f32_16x16x32_bf16 v[126:129], v[110:113], v[94:97], v[126:129]
	s_waitcnt vmcnt(11)
	ds_write_b128 v22, v[182:185]
	s_waitcnt vmcnt(7)
	ds_write_b128 v23, v[198:201]
	s_waitcnt lgkmcnt(12)
	v_mfma_f32_16x16x32_bf16 v[130:133], v[114:117], v[94:97], v[130:133]
	s_waitcnt lgkmcnt(11)
	v_mfma_f32_16x16x32_bf16 v[134:137], v[118:121], v[94:97], v[134:137]
	s_waitcnt lgkmcnt(10)
	v_mfma_f32_16x16x32_bf16 v[42:45], v[122:125], v[94:97], v[42:45]
	v_mfma_f32_16x16x32_bf16 v[58:61], v[110:113], v[98:101], v[58:61]
	ds_write_b128 v22, v[186:189] offset:10240
	s_waitcnt vmcnt(6)
	ds_write_b128 v25, v[202:205]
	v_mfma_f32_16x16x32_bf16 v[62:65], v[114:117], v[98:101], v[62:65]
	v_mfma_f32_16x16x32_bf16 v[74:77], v[118:121], v[98:101], v[74:77]
	v_mfma_f32_16x16x32_bf16 v[46:49], v[122:125], v[98:101], v[46:49]
	v_mfma_f32_16x16x32_bf16 v[66:69], v[110:113], v[102:105], v[66:69]
	ds_write_b128 v22, v[190:193] offset:20480
	v_mfma_f32_16x16x32_bf16 v[78:81], v[114:117], v[102:105], v[78:81]
	v_mfma_f32_16x16x32_bf16 v[82:85], v[118:121], v[102:105], v[82:85]
	v_mfma_f32_16x16x32_bf16 v[50:53], v[122:125], v[102:105], v[50:53]
	v_mfma_f32_16x16x32_bf16 v[70:73], v[110:113], v[106:109], v[70:73]
	ds_write_b128 v22, v[194:197] offset:30720
	v_mfma_f32_16x16x32_bf16 v[86:89], v[114:117], v[106:109], v[86:89]
	v_mfma_f32_16x16x32_bf16 v[90:93], v[118:121], v[106:109], v[90:93]
	v_mfma_f32_16x16x32_bf16 v[54:57], v[122:125], v[106:109], v[54:57]
	s_waitcnt lgkmcnt(0)
	s_barrier
	ds_read_b128 v[94:97], v39
	ds_read_b128 v[98:101], v39 offset:2560
	ds_read_b128 v[102:105], v39 offset:5120
	ds_read_b128 v[106:109], v39 offset:7680
	ds_read_b128 v[110:113], v40 offset:40960
	ds_read_b128 v[114:117], v40 offset:43520
	ds_read_b128 v[118:121], v40 offset:46080
	ds_read_b128 v[122:125], v40 offset:48640
	v_mfma_f32_16x16x32_bf16 v[126:129], v[222:225], v[206:209], v[126:129]
	v_mfma_f32_16x16x32_bf16 v[130:133], v[226:229], v[206:209], v[130:133]
	v_mfma_f32_16x16x32_bf16 v[134:137], v[230:233], v[206:209], v[134:137]
	v_mfma_f32_16x16x32_bf16 v[42:45], v[234:237], v[206:209], v[42:45]
	v_mfma_f32_16x16x32_bf16 v[58:61], v[222:225], v[210:213], v[58:61]
	v_mfma_f32_16x16x32_bf16 v[62:65], v[226:229], v[210:213], v[62:65]
	v_mfma_f32_16x16x32_bf16 v[74:77], v[230:233], v[210:213], v[74:77]
	v_mfma_f32_16x16x32_bf16 v[46:49], v[234:237], v[210:213], v[46:49]
	v_mfma_f32_16x16x32_bf16 v[66:69], v[222:225], v[214:217], v[66:69]
	v_mfma_f32_16x16x32_bf16 v[78:81], v[226:229], v[214:217], v[78:81]
	v_mfma_f32_16x16x32_bf16 v[82:85], v[230:233], v[214:217], v[82:85]
	v_mfma_f32_16x16x32_bf16 v[50:53], v[234:237], v[214:217], v[50:53]
	v_mfma_f32_16x16x32_bf16 v[70:73], v[222:225], v[218:221], v[70:73]
	v_mfma_f32_16x16x32_bf16 v[86:89], v[226:229], v[218:221], v[86:89]
	v_mfma_f32_16x16x32_bf16 v[90:93], v[230:233], v[218:221], v[90:93]
	v_mfma_f32_16x16x32_bf16 v[54:57], v[234:237], v[218:221], v[54:57]
	global_load_dwordx4 v[182:185], v[2:3], off offset:768
	global_load_dwordx4 v[186:189], v[8:9], off offset:768
	global_load_dwordx4 v[190:193], v[10:11], off offset:768
	global_load_dwordx4 v[194:197], v[12:13], off offset:768
	global_load_dwordx4 v[198:201], v[14:15], off offset:768
	global_load_dwordx4 v[202:205], v[16:17], off offset:768
	ds_read_b128 v[206:209], v30 offset:64
	ds_read_b128 v[210:213], v30 offset:2624
	ds_read_b128 v[214:217], v30 offset:5184
	ds_read_b128 v[218:221], v30 offset:7744
	ds_read_b128 v[222:225], v31 offset:41024
	ds_read_b128 v[226:229], v31 offset:43584
	ds_read_b128 v[230:233], v31 offset:46144
	ds_read_b128 v[234:237], v31 offset:48704
	s_waitcnt lgkmcnt(11)
;     ...
;   for (int k0 = 0; k0 < K; k0 += 128) {
;     G_READ(fa1, fb1, 0, 32);
;     if (k0 + 128 < K) G_LOAD(ra0, rb0, k0 + 128);
;     __builtin_amdgcn_sched_barrier(0);
;     G_MFMA_ST(fa0, fb0, ra1, rb1, 1);
;     __syncthreads();
;     G_READ(fa0, fb0, 1, 0);
;     __builtin_amdgcn_sched_barrier(0);
;     G_MFMA(fa1, fb1);
;     __builtin_amdgcn_sched_barrier(0);
;     G_READ(fa1, fb1, 1, 32);
;     if (k0 + 192 < K) G_LOAD(ra1, rb1, k0 + 192);
;     __builtin_amdgcn_sched_barrier(0);
;     if (k0 + 128 < K) {
;       G_MFMA_ST(fa0, fb0, ra0, rb0, 0);
;       __syncthreads();
;       G_READ(fa0, fb0, 0, 0);
;     } else {
;       G_MFMA(fa0, fb0);
;     }
;     __builtin_amdgcn_sched_barrier(0);
;     G_MFMA(fa1, fb1);
;     __builtin_amdgcn_sched_barrier(0);
;   }
	v_mfma_f32_16x16x32_bf16 v[126:129], v[110:113], v[94:97], v[126:129]
	s_waitcnt vmcnt(11)
	ds_write_b128 v22, v[138:141] offset:61440
	s_waitcnt vmcnt(7)
	ds_write_b128 v23, v[174:177] offset:61440
	s_waitcnt lgkmcnt(12)
	v_mfma_f32_16x16x32_bf16 v[130:133], v[114:117], v[94:97], v[130:133]
	s_waitcnt lgkmcnt(11)
	v_mfma_f32_16x16x32_bf16 v[134:137], v[118:121], v[94:97], v[134:137]
	s_waitcnt lgkmcnt(10)
	v_mfma_f32_16x16x32_bf16 v[42:45], v[122:125], v[94:97], v[42:45]
	v_mfma_f32_16x16x32_bf16 v[58:61], v[110:113], v[98:101], v[58:61]
	ds_write_b128 v24, v[142:145] offset:61440
	s_waitcnt vmcnt(6)
	ds_write_b128 v25, v[178:181] offset:61440
	v_mfma_f32_16x16x32_bf16 v[62:65], v[114:117], v[98:101], v[62:65]
	v_mfma_f32_16x16x32_bf16 v[74:77], v[118:121], v[98:101], v[74:77]
	v_mfma_f32_16x16x32_bf16 v[46:49], v[122:125], v[98:101], v[46:49]
	v_mfma_f32_16x16x32_bf16 v[66:69], v[110:113], v[102:105], v[66:69]
	ds_write_b128 v26, v[152:155] offset:61440
	v_mfma_f32_16x16x32_bf16 v[78:81], v[114:117], v[102:105], v[78:81]
	v_mfma_f32_16x16x32_bf16 v[82:85], v[118:121], v[102:105], v[82:85]
	v_mfma_f32_16x16x32_bf16 v[50:53], v[122:125], v[102:105], v[50:53]
	v_mfma_f32_16x16x32_bf16 v[70:73], v[110:113], v[106:109], v[70:73]
	ds_write_b128 v27, v[156:159] offset:61440
	v_mfma_f32_16x16x32_bf16 v[86:89], v[114:117], v[106:109], v[86:89]
	v_mfma_f32_16x16x32_bf16 v[90:93], v[118:121], v[106:109], v[90:93]
	v_mfma_f32_16x16x32_bf16 v[54:57], v[122:125], v[106:109], v[54:57]
	s_waitcnt lgkmcnt(0)
	s_barrier
	ds_read_b128 v[94:97], v39 offset:61440
	ds_read_b128 v[98:101], v39 offset:64000
	ds_read_b128 v[102:105], v32 offset:5120
	ds_read_b128 v[106:109], v32 offset:7680
	ds_read_b128 v[110:113], v33
	ds_read_b128 v[114:117], v33 offset:2560
	ds_read_b128 v[118:121], v33 offset:5120
	ds_read_b128 v[122:125], v33 offset:7680
	v_mfma_f32_16x16x32_bf16 v[126:129], v[222:225], v[206:209], v[126:129]
	v_mfma_f32_16x16x32_bf16 v[130:133], v[226:229], v[206:209], v[130:133]
	v_mfma_f32_16x16x32_bf16 v[134:137], v[230:233], v[206:209], v[134:137]
	v_mfma_f32_16x16x32_bf16 v[42:45], v[234:237], v[206:209], v[42:45]
	v_mfma_f32_16x16x32_bf16 v[58:61], v[222:225], v[210:213], v[58:61]
	v_mfma_f32_16x16x32_bf16 v[62:65], v[226:229], v[210:213], v[62:65]
	v_mfma_f32_16x16x32_bf16 v[74:77], v[230:233], v[210:213], v[74:77]
	v_mfma_f32_16x16x32_bf16 v[46:49], v[234:237], v[210:213], v[46:49]
	v_mfma_f32_16x16x32_bf16 v[66:69], v[222:225], v[214:217], v[66:69]
	v_mfma_f32_16x16x32_bf16 v[78:81], v[226:229], v[214:217], v[78:81]
	v_mfma_f32_16x16x32_bf16 v[82:85], v[230:233], v[214:217], v[82:85]
	v_mfma_f32_16x16x32_bf16 v[50:53], v[234:237], v[214:217], v[50:53]
	v_mfma_f32_16x16x32_bf16 v[70:73], v[222:225], v[218:221], v[70:73]
	v_mfma_f32_16x16x32_bf16 v[86:89], v[226:229], v[218:221], v[86:89]
	v_mfma_f32_16x16x32_bf16 v[90:93], v[230:233], v[218:221], v[90:93]
	v_mfma_f32_16x16x32_bf16 v[54:57], v[234:237], v[218:221], v[54:57]
	global_load_dwordx4 v[138:141], v[2:3], off offset:896
	global_load_dwordx4 v[142:145], v[8:9], off offset:896
	global_load_dwordx4 v[152:155], v[10:11], off offset:896
	global_load_dwordx4 v[156:159], v[12:13], off offset:896
	global_load_dwordx4 v[174:177], v[14:15], off offset:896
	global_load_dwordx4 v[178:181], v[16:17], off offset:896
	ds_read_b128 v[206:209], v30 offset:61504
	ds_read_b128 v[210:213], v30 offset:64064
	ds_read_b128 v[214:217], v34 offset:64
	ds_read_b128 v[218:221], v35 offset:64
	ds_read_b128 v[222:225], v41 offset:64
	ds_read_b128 v[226:229], v36 offset:64
	ds_read_b128 v[230:233], v37 offset:64
	ds_read_b128 v[234:237], v38 offset:64
	s_waitcnt lgkmcnt(11)
	v_mfma_f32_16x16x32_bf16 v[126:129], v[110:113], v[94:97], v[126:129]
	s_waitcnt vmcnt(11)
	ds_write_b128 v22, v[182:185]
	s_waitcnt vmcnt(7)
	ds_write_b128 v23, v[198:201]
	s_waitcnt lgkmcnt(12)
	v_mfma_f32_16x16x32_bf16 v[130:133], v[114:117], v[94:97], v[130:133]
	s_waitcnt lgkmcnt(11)
	v_mfma_f32_16x16x32_bf16 v[134:137], v[118:121], v[94:97], v[134:137]
	s_waitcnt lgkmcnt(10)
	v_mfma_f32_16x16x32_bf16 v[42:45], v[122:125], v[94:97], v[42:45]
	v_mfma_f32_16x16x32_bf16 v[58:61], v[110:113], v[98:101], v[58:61]
	ds_write_b128 v22, v[186:189] offset:10240
	s_waitcnt vmcnt(6)
	ds_write_b128 v25, v[202:205]
	v_mfma_f32_16x16x32_bf16 v[62:65], v[114:117], v[98:101], v[62:65]
	v_mfma_f32_16x16x32_bf16 v[74:77], v[118:121], v[98:101], v[74:77]
	v_mfma_f32_16x16x32_bf16 v[46:49], v[122:125], v[98:101], v[46:49]
	v_mfma_f32_16x16x32_bf16 v[66:69], v[110:113], v[102:105], v[66:69]
	ds_write_b128 v22, v[190:193] offset:20480
	v_mfma_f32_16x16x32_bf16 v[78:81], v[114:117], v[102:105], v[78:81]
	v_mfma_f32_16x16x32_bf16 v[82:85], v[118:121], v[102:105], v[82:85]
	v_mfma_f32_16x16x32_bf16 v[50:53], v[122:125], v[102:105], v[50:53]
	v_mfma_f32_16x16x32_bf16 v[70:73], v[110:113], v[106:109], v[70:73]
	ds_write_b128 v22, v[194:197] offset:30720
	v_mfma_f32_16x16x32_bf16 v[86:89], v[114:117], v[106:109], v[86:89]
	v_mfma_f32_16x16x32_bf16 v[90:93], v[118:121], v[106:109], v[90:93]
	v_mfma_f32_16x16x32_bf16 v[54:57], v[122:125], v[106:109], v[54:57]
	s_waitcnt lgkmcnt(0)
	s_barrier
;     ...
;   for (int k0 = 0; k0 < K; k0 += 128) {
;     G_READ(fa1, fb1, 0, 32);
;     if (k0 + 128 < K) G_LOAD(ra0, rb0, k0 + 128);
;     __builtin_amdgcn_sched_barrier(0);
;     G_MFMA_ST(fa0, fb0, ra1, rb1, 1);
;     __syncthreads();
;     G_READ(fa0, fb0, 1, 0);
;     __builtin_amdgcn_sched_barrier(0);
;     G_MFMA(fa1, fb1);
;     __builtin_amdgcn_sched_barrier(0);
;     G_READ(fa1, fb1, 1, 32);
;     if (k0 + 192 < K) G_LOAD(ra1, rb1, k0 + 192);
;     __builtin_amdgcn_sched_barrier(0);
;     if (k0 + 128 < K) {
;       G_MFMA_ST(fa0, fb0, ra0, rb0, 0);
;       __syncthreads();
;       G_READ(fa0, fb0, 0, 0);
;     } else {
;       G_MFMA(fa0, fb0);
;     }
;     __builtin_amdgcn_sched_barrier(0);
;     G_MFMA(fa1, fb1);
;     __builtin_amdgcn_sched_barrier(0);
;   }
	ds_read_b128 v[94:97], v39
	ds_read_b128 v[98:101], v39 offset:2560
	ds_read_b128 v[102:105], v39 offset:5120
	ds_read_b128 v[106:109], v39 offset:7680
	ds_read_b128 v[110:113], v40 offset:40960
	ds_read_b128 v[114:117], v40 offset:43520
	ds_read_b128 v[118:121], v40 offset:46080
	ds_read_b128 v[122:125], v40 offset:48640
	v_mfma_f32_16x16x32_bf16 v[126:129], v[222:225], v[206:209], v[126:129]
	v_mfma_f32_16x16x32_bf16 v[130:133], v[226:229], v[206:209], v[130:133]
	v_mfma_f32_16x16x32_bf16 v[134:137], v[230:233], v[206:209], v[134:137]
	v_mfma_f32_16x16x32_bf16 v[42:45], v[234:237], v[206:209], v[42:45]
	v_mfma_f32_16x16x32_bf16 v[58:61], v[222:225], v[210:213], v[58:61]
	v_mfma_f32_16x16x32_bf16 v[62:65], v[226:229], v[210:213], v[62:65]
	v_mfma_f32_16x16x32_bf16 v[74:77], v[230:233], v[210:213], v[74:77]
	v_mfma_f32_16x16x32_bf16 v[46:49], v[234:237], v[210:213], v[46:49]
	v_mfma_f32_16x16x32_bf16 v[66:69], v[222:225], v[214:217], v[66:69]
	v_mfma_f32_16x16x32_bf16 v[78:81], v[226:229], v[214:217], v[78:81]
	v_mfma_f32_16x16x32_bf16 v[82:85], v[230:233], v[214:217], v[82:85]
	v_mfma_f32_16x16x32_bf16 v[50:53], v[234:237], v[214:217], v[50:53]
	v_mfma_f32_16x16x32_bf16 v[70:73], v[222:225], v[218:221], v[70:73]
	v_mfma_f32_16x16x32_bf16 v[86:89], v[226:229], v[218:221], v[86:89]
	v_mfma_f32_16x16x32_bf16 v[90:93], v[230:233], v[218:221], v[90:93]
	v_mfma_f32_16x16x32_bf16 v[54:57], v[234:237], v[218:221], v[54:57]
	global_load_dwordx4 v[182:185], v[2:3], off offset:1024
	global_load_dwordx4 v[186:189], v[8:9], off offset:1024
	global_load_dwordx4 v[190:193], v[10:11], off offset:1024
	global_load_dwordx4 v[194:197], v[12:13], off offset:1024
	global_load_dwordx4 v[198:201], v[14:15], off offset:1024
	global_load_dwordx4 v[202:205], v[16:17], off offset:1024
	ds_read_b128 v[206:209], v30 offset:64
	ds_read_b128 v[210:213], v30 offset:2624
	ds_read_b128 v[214:217], v30 offset:5184
	ds_read_b128 v[218:221], v30 offset:7744
	ds_read_b128 v[222:225], v31 offset:41024
	ds_read_b128 v[226:229], v31 offset:43584
	ds_read_b128 v[230:233], v31 offset:46144
	ds_read_b128 v[234:237], v31 offset:48704
	s_waitcnt lgkmcnt(11)
	v_mfma_f32_16x16x32_bf16 v[126:129], v[110:113], v[94:97], v[126:129]
	s_waitcnt vmcnt(11)
	ds_write_b128 v22, v[138:141] offset:61440
	s_waitcnt vmcnt(7)
	ds_write_b128 v23, v[174:177] offset:61440
	s_waitcnt lgkmcnt(12)
	v_mfma_f32_16x16x32_bf16 v[130:133], v[114:117], v[94:97], v[130:133]
	s_waitcnt lgkmcnt(11)
	v_mfma_f32_16x16x32_bf16 v[134:137], v[118:121], v[94:97], v[134:137]
	s_waitcnt lgkmcnt(10)
	v_mfma_f32_16x16x32_bf16 v[42:45], v[122:125], v[94:97], v[42:45]
	v_mfma_f32_16x16x32_bf16 v[58:61], v[110:113], v[98:101], v[58:61]
	ds_write_b128 v24, v[142:145] offset:61440
	s_waitcnt vmcnt(6)
	ds_write_b128 v25, v[178:181] offset:61440
	v_mfma_f32_16x16x32_bf16 v[62:65], v[114:117], v[98:101], v[62:65]
	v_mfma_f32_16x16x32_bf16 v[74:77], v[118:121], v[98:101], v[74:77]
	v_mfma_f32_16x16x32_bf16 v[46:49], v[122:125], v[98:101], v[46:49]
	v_mfma_f32_16x16x32_bf16 v[66:69], v[110:113], v[102:105], v[66:69]
	ds_write_b128 v26, v[152:155] offset:61440
	v_mfma_f32_16x16x32_bf16 v[78:81], v[114:117], v[102:105], v[78:81]
	v_mfma_f32_16x16x32_bf16 v[82:85], v[118:121], v[102:105], v[82:85]
	v_mfma_f32_16x16x32_bf16 v[50:53], v[122:125], v[102:105], v[50:53]
	v_mfma_f32_16x16x32_bf16 v[70:73], v[110:113], v[106:109], v[70:73]
	ds_write_b128 v27, v[156:159] offset:61440
	v_mfma_f32_16x16x32_bf16 v[86:89], v[114:117], v[106:109], v[86:89]
	v_mfma_f32_16x16x32_bf16 v[90:93], v[118:121], v[106:109], v[90:93]
	v_mfma_f32_16x16x32_bf16 v[54:57], v[122:125], v[106:109], v[54:57]
	s_waitcnt lgkmcnt(0)
	s_barrier
	ds_read_b128 v[94:97], v39 offset:61440
	ds_read_b128 v[98:101], v39 offset:64000
	ds_read_b128 v[102:105], v32 offset:5120
	ds_read_b128 v[106:109], v32 offset:7680
	ds_read_b128 v[110:113], v33
	ds_read_b128 v[114:117], v33 offset:2560
	ds_read_b128 v[118:121], v33 offset:5120
	ds_read_b128 v[122:125], v33 offset:7680
	v_mfma_f32_16x16x32_bf16 v[126:129], v[222:225], v[206:209], v[126:129]
	v_mfma_f32_16x16x32_bf16 v[130:133], v[226:229], v[206:209], v[130:133]
	v_mfma_f32_16x16x32_bf16 v[134:137], v[230:233], v[206:209], v[134:137]
	v_mfma_f32_16x16x32_bf16 v[42:45], v[234:237], v[206:209], v[42:45]
	v_mfma_f32_16x16x32_bf16 v[58:61], v[222:225], v[210:213], v[58:61]
	v_mfma_f32_16x16x32_bf16 v[62:65], v[226:229], v[210:213], v[62:65]
	v_mfma_f32_16x16x32_bf16 v[74:77], v[230:233], v[210:213], v[74:77]
	v_mfma_f32_16x16x32_bf16 v[46:49], v[234:237], v[210:213], v[46:49]
	v_mfma_f32_16x16x32_bf16 v[66:69], v[222:225], v[214:217], v[66:69]
	v_mfma_f32_16x16x32_bf16 v[78:81], v[226:229], v[214:217], v[78:81]
	v_mfma_f32_16x16x32_bf16 v[82:85], v[230:233], v[214:217], v[82:85]
	v_mfma_f32_16x16x32_bf16 v[50:53], v[234:237], v[214:217], v[50:53]
	v_mfma_f32_16x16x32_bf16 v[70:73], v[222:225], v[218:221], v[70:73]
	v_mfma_f32_16x16x32_bf16 v[86:89], v[226:229], v[218:221], v[86:89]
	v_mfma_f32_16x16x32_bf16 v[90:93], v[230:233], v[218:221], v[90:93]
	v_mfma_f32_16x16x32_bf16 v[54:57], v[234:237], v[218:221], v[54:57]
	global_load_dwordx4 v[138:141], v[2:3], off offset:1152
	global_load_dwordx4 v[142:145], v[8:9], off offset:1152
	global_load_dwordx4 v[152:155], v[10:11], off offset:1152
	global_load_dwordx4 v[156:159], v[12:13], off offset:1152
	global_load_dwordx4 v[174:177], v[14:15], off offset:1152
	global_load_dwordx4 v[178:181], v[16:17], off offset:1152
	ds_read_b128 v[206:209], v30 offset:61504
	ds_read_b128 v[210:213], v30 offset:64064
	ds_read_b128 v[214:217], v34 offset:64
	ds_read_b128 v[218:221], v35 offset:64
	ds_read_b128 v[222:225], v41 offset:64
	ds_read_b128 v[226:229], v36 offset:64
	ds_read_b128 v[230:233], v37 offset:64
	ds_read_b128 v[234:237], v38 offset:64
	s_waitcnt lgkmcnt(11)
;     ...
;   for (int k0 = 0; k0 < K; k0 += 128) {
;     G_READ(fa1, fb1, 0, 32);
;     if (k0 + 128 < K) G_LOAD(ra0, rb0, k0 + 128);
;     __builtin_amdgcn_sched_barrier(0);
;     G_MFMA_ST(fa0, fb0, ra1, rb1, 1);
;     __syncthreads();
;     G_READ(fa0, fb0, 1, 0);
;     __builtin_amdgcn_sched_barrier(0);
;     G_MFMA(fa1, fb1);
;     __builtin_amdgcn_sched_barrier(0);
;     G_READ(fa1, fb1, 1, 32);
;     if (k0 + 192 < K) G_LOAD(ra1, rb1, k0 + 192);
;     __builtin_amdgcn_sched_barrier(0);
;     if (k0 + 128 < K) {
;       G_MFMA_ST(fa0, fb0, ra0, rb0, 0);
;       __syncthreads();
;       G_READ(fa0, fb0, 0, 0);
;     } else {
;       G_MFMA(fa0, fb0);
;     }
;     __builtin_amdgcn_sched_barrier(0);
;     G_MFMA(fa1, fb1);
;     __builtin_amdgcn_sched_barrier(0);
;   }
	v_mfma_f32_16x16x32_bf16 v[126:129], v[110:113], v[94:97], v[126:129]
	s_waitcnt vmcnt(11)
	ds_write_b128 v22, v[182:185]
	s_waitcnt vmcnt(7)
	ds_write_b128 v23, v[198:201]
	s_waitcnt lgkmcnt(12)
	v_mfma_f32_16x16x32_bf16 v[130:133], v[114:117], v[94:97], v[130:133]
	s_waitcnt lgkmcnt(11)
	v_mfma_f32_16x16x32_bf16 v[134:137], v[118:121], v[94:97], v[134:137]
	s_waitcnt lgkmcnt(10)
	v_mfma_f32_16x16x32_bf16 v[42:45], v[122:125], v[94:97], v[42:45]
	v_mfma_f32_16x16x32_bf16 v[58:61], v[110:113], v[98:101], v[58:61]
	ds_write_b128 v22, v[186:189] offset:10240
	s_waitcnt vmcnt(6)
	ds_write_b128 v25, v[202:205]
	v_mfma_f32_16x16x32_bf16 v[62:65], v[114:117], v[98:101], v[62:65]
	v_mfma_f32_16x16x32_bf16 v[74:77], v[118:121], v[98:101], v[74:77]
	v_mfma_f32_16x16x32_bf16 v[46:49], v[122:125], v[98:101], v[46:49]
	v_mfma_f32_16x16x32_bf16 v[66:69], v[110:113], v[102:105], v[66:69]
	ds_write_b128 v22, v[190:193] offset:20480
	v_mfma_f32_16x16x32_bf16 v[78:81], v[114:117], v[102:105], v[78:81]
	v_mfma_f32_16x16x32_bf16 v[82:85], v[118:121], v[102:105], v[82:85]
	v_mfma_f32_16x16x32_bf16 v[50:53], v[122:125], v[102:105], v[50:53]
	v_mfma_f32_16x16x32_bf16 v[70:73], v[110:113], v[106:109], v[70:73]
	ds_write_b128 v22, v[194:197] offset:30720
	v_mfma_f32_16x16x32_bf16 v[86:89], v[114:117], v[106:109], v[86:89]
	v_mfma_f32_16x16x32_bf16 v[90:93], v[118:121], v[106:109], v[90:93]
	v_mfma_f32_16x16x32_bf16 v[54:57], v[122:125], v[106:109], v[54:57]
	s_waitcnt lgkmcnt(0)
	s_barrier
	ds_read_b128 v[94:97], v39
	ds_read_b128 v[98:101], v39 offset:2560
	ds_read_b128 v[102:105], v39 offset:5120
	ds_read_b128 v[106:109], v39 offset:7680
	ds_read_b128 v[110:113], v40 offset:40960
	ds_read_b128 v[114:117], v40 offset:43520
	ds_read_b128 v[118:121], v40 offset:46080
	ds_read_b128 v[122:125], v40 offset:48640
	v_mfma_f32_16x16x32_bf16 v[126:129], v[222:225], v[206:209], v[126:129]
	v_mfma_f32_16x16x32_bf16 v[130:133], v[226:229], v[206:209], v[130:133]
	v_mfma_f32_16x16x32_bf16 v[134:137], v[230:233], v[206:209], v[134:137]
	v_mfma_f32_16x16x32_bf16 v[42:45], v[234:237], v[206:209], v[42:45]
	v_mfma_f32_16x16x32_bf16 v[58:61], v[222:225], v[210:213], v[58:61]
	v_mfma_f32_16x16x32_bf16 v[62:65], v[226:229], v[210:213], v[62:65]
	v_mfma_f32_16x16x32_bf16 v[74:77], v[230:233], v[210:213], v[74:77]
	v_mfma_f32_16x16x32_bf16 v[46:49], v[234:237], v[210:213], v[46:49]
	v_mfma_f32_16x16x32_bf16 v[66:69], v[222:225], v[214:217], v[66:69]
	v_mfma_f32_16x16x32_bf16 v[78:81], v[226:229], v[214:217], v[78:81]
	v_mfma_f32_16x16x32_bf16 v[82:85], v[230:233], v[214:217], v[82:85]
	v_mfma_f32_16x16x32_bf16 v[50:53], v[234:237], v[214:217], v[50:53]
	v_mfma_f32_16x16x32_bf16 v[70:73], v[222:225], v[218:221], v[70:73]
	v_mfma_f32_16x16x32_bf16 v[86:89], v[226:229], v[218:221], v[86:89]
	v_mfma_f32_16x16x32_bf16 v[90:93], v[230:233], v[218:221], v[90:93]
	v_mfma_f32_16x16x32_bf16 v[54:57], v[234:237], v[218:221], v[54:57]
	global_load_dwordx4 v[182:185], v[2:3], off offset:1280
	global_load_dwordx4 v[186:189], v[8:9], off offset:1280
	global_load_dwordx4 v[190:193], v[10:11], off offset:1280
	global_load_dwordx4 v[194:197], v[12:13], off offset:1280
	global_load_dwordx4 v[198:201], v[14:15], off offset:1280
	global_load_dwordx4 v[202:205], v[16:17], off offset:1280
	ds_read_b128 v[206:209], v30 offset:64
	ds_read_b128 v[210:213], v30 offset:2624
	ds_read_b128 v[214:217], v30 offset:5184
	ds_read_b128 v[218:221], v30 offset:7744
	ds_read_b128 v[222:225], v31 offset:41024
	ds_read_b128 v[226:229], v31 offset:43584
	ds_read_b128 v[230:233], v31 offset:46144
	ds_read_b128 v[234:237], v31 offset:48704
	s_waitcnt lgkmcnt(11)
	v_mfma_f32_16x16x32_bf16 v[126:129], v[110:113], v[94:97], v[126:129]
	s_waitcnt vmcnt(11)
	ds_write_b128 v22, v[138:141] offset:61440
	s_waitcnt vmcnt(7)
	ds_write_b128 v23, v[174:177] offset:61440
	s_waitcnt lgkmcnt(12)
	v_mfma_f32_16x16x32_bf16 v[130:133], v[114:117], v[94:97], v[130:133]
	s_waitcnt lgkmcnt(11)
	v_mfma_f32_16x16x32_bf16 v[134:137], v[118:121], v[94:97], v[134:137]
	s_waitcnt lgkmcnt(10)
	v_mfma_f32_16x16x32_bf16 v[42:45], v[122:125], v[94:97], v[42:45]
	v_mfma_f32_16x16x32_bf16 v[58:61], v[110:113], v[98:101], v[58:61]
	ds_write_b128 v24, v[142:145] offset:61440
	s_waitcnt vmcnt(6)
	ds_write_b128 v25, v[178:181] offset:61440
	v_mfma_f32_16x16x32_bf16 v[62:65], v[114:117], v[98:101], v[62:65]
	v_mfma_f32_16x16x32_bf16 v[74:77], v[118:121], v[98:101], v[74:77]
	v_mfma_f32_16x16x32_bf16 v[46:49], v[122:125], v[98:101], v[46:49]
	v_mfma_f32_16x16x32_bf16 v[66:69], v[110:113], v[102:105], v[66:69]
	ds_write_b128 v26, v[152:155] offset:61440
	v_mfma_f32_16x16x32_bf16 v[78:81], v[114:117], v[102:105], v[78:81]
	v_mfma_f32_16x16x32_bf16 v[82:85], v[118:121], v[102:105], v[82:85]
	v_mfma_f32_16x16x32_bf16 v[50:53], v[122:125], v[102:105], v[50:53]
	v_mfma_f32_16x16x32_bf16 v[70:73], v[110:113], v[106:109], v[70:73]
	ds_write_b128 v27, v[156:159] offset:61440
	v_mfma_f32_16x16x32_bf16 v[86:89], v[114:117], v[106:109], v[86:89]
	v_mfma_f32_16x16x32_bf16 v[90:93], v[118:121], v[106:109], v[90:93]
	v_mfma_f32_16x16x32_bf16 v[54:57], v[122:125], v[106:109], v[54:57]
	s_waitcnt lgkmcnt(0)
	s_barrier
;     ...
;   for (int k0 = 0; k0 < K; k0 += 128) {
;     G_READ(fa1, fb1, 0, 32);
;     if (k0 + 128 < K) G_LOAD(ra0, rb0, k0 + 128);
;     __builtin_amdgcn_sched_barrier(0);
;     G_MFMA_ST(fa0, fb0, ra1, rb1, 1);
;     __syncthreads();
;     G_READ(fa0, fb0, 1, 0);
;     __builtin_amdgcn_sched_barrier(0);
;     G_MFMA(fa1, fb1);
;     __builtin_amdgcn_sched_barrier(0);
;     G_READ(fa1, fb1, 1, 32);
;     if (k0 + 192 < K) G_LOAD(ra1, rb1, k0 + 192);
;     __builtin_amdgcn_sched_barrier(0);
;     if (k0 + 128 < K) {
;       G_MFMA_ST(fa0, fb0, ra0, rb0, 0);
;       __syncthreads();
;       G_READ(fa0, fb0, 0, 0);
;     } else {
;       G_MFMA(fa0, fb0);
;     }
;     __builtin_amdgcn_sched_barrier(0);
;     G_MFMA(fa1, fb1);
;     __builtin_amdgcn_sched_barrier(0);
;   }
	ds_read_b128 v[94:97], v39 offset:61440
	ds_read_b128 v[98:101], v39 offset:64000
	ds_read_b128 v[102:105], v32 offset:5120
	ds_read_b128 v[106:109], v32 offset:7680
	ds_read_b128 v[110:113], v33
	ds_read_b128 v[114:117], v33 offset:2560
	ds_read_b128 v[118:121], v33 offset:5120
	ds_read_b128 v[122:125], v33 offset:7680
	v_mfma_f32_16x16x32_bf16 v[126:129], v[222:225], v[206:209], v[126:129]
	v_mfma_f32_16x16x32_bf16 v[130:133], v[226:229], v[206:209], v[130:133]
	v_mfma_f32_16x16x32_bf16 v[134:137], v[230:233], v[206:209], v[134:137]
	v_mfma_f32_16x16x32_bf16 v[42:45], v[234:237], v[206:209], v[42:45]
	v_mfma_f32_16x16x32_bf16 v[58:61], v[222:225], v[210:213], v[58:61]
	v_mfma_f32_16x16x32_bf16 v[62:65], v[226:229], v[210:213], v[62:65]
	v_mfma_f32_16x16x32_bf16 v[74:77], v[230:233], v[210:213], v[74:77]
	v_mfma_f32_16x16x32_bf16 v[46:49], v[234:237], v[210:213], v[46:49]
	v_mfma_f32_16x16x32_bf16 v[66:69], v[222:225], v[214:217], v[66:69]
	v_mfma_f32_16x16x32_bf16 v[78:81], v[226:229], v[214:217], v[78:81]
	v_mfma_f32_16x16x32_bf16 v[82:85], v[230:233], v[214:217], v[82:85]
	v_mfma_f32_16x16x32_bf16 v[50:53], v[234:237], v[214:217], v[50:53]
	v_mfma_f32_16x16x32_bf16 v[70:73], v[222:225], v[218:221], v[70:73]
	v_mfma_f32_16x16x32_bf16 v[86:89], v[226:229], v[218:221], v[86:89]
	v_mfma_f32_16x16x32_bf16 v[90:93], v[230:233], v[218:221], v[90:93]
	v_mfma_f32_16x16x32_bf16 v[54:57], v[234:237], v[218:221], v[54:57]
	global_load_dwordx4 v[138:141], v[2:3], off offset:1408
	global_load_dwordx4 v[142:145], v[8:9], off offset:1408
	global_load_dwordx4 v[152:155], v[10:11], off offset:1408
	global_load_dwordx4 v[156:159], v[12:13], off offset:1408
	global_load_dwordx4 v[174:177], v[14:15], off offset:1408
	global_load_dwordx4 v[178:181], v[16:17], off offset:1408
	ds_read_b128 v[206:209], v30 offset:61504
	ds_read_b128 v[210:213], v30 offset:64064
	ds_read_b128 v[214:217], v34 offset:64
	ds_read_b128 v[218:221], v35 offset:64
	ds_read_b128 v[222:225], v41 offset:64
	ds_read_b128 v[226:229], v36 offset:64
	ds_read_b128 v[230:233], v37 offset:64
	ds_read_b128 v[234:237], v38 offset:64
	s_waitcnt lgkmcnt(11)
	v_mfma_f32_16x16x32_bf16 v[126:129], v[110:113], v[94:97], v[126:129]
	s_waitcnt vmcnt(11)
	ds_write_b128 v22, v[182:185]
	s_waitcnt vmcnt(7)
	ds_write_b128 v23, v[198:201]
	s_waitcnt lgkmcnt(12)
	v_mfma_f32_16x16x32_bf16 v[130:133], v[114:117], v[94:97], v[130:133]
	s_waitcnt lgkmcnt(11)
	v_mfma_f32_16x16x32_bf16 v[134:137], v[118:121], v[94:97], v[134:137]
	s_waitcnt lgkmcnt(10)
	v_mfma_f32_16x16x32_bf16 v[42:45], v[122:125], v[94:97], v[42:45]
	v_mfma_f32_16x16x32_bf16 v[58:61], v[110:113], v[98:101], v[58:61]
	ds_write_b128 v22, v[186:189] offset:10240
	s_waitcnt vmcnt(6)
	ds_write_b128 v25, v[202:205]
	v_mfma_f32_16x16x32_bf16 v[62:65], v[114:117], v[98:101], v[62:65]
	v_mfma_f32_16x16x32_bf16 v[74:77], v[118:121], v[98:101], v[74:77]
	v_mfma_f32_16x16x32_bf16 v[46:49], v[122:125], v[98:101], v[46:49]
	v_mfma_f32_16x16x32_bf16 v[66:69], v[110:113], v[102:105], v[66:69]
	ds_write_b128 v22, v[190:193] offset:20480
	v_mfma_f32_16x16x32_bf16 v[78:81], v[114:117], v[102:105], v[78:81]
	v_mfma_f32_16x16x32_bf16 v[82:85], v[118:121], v[102:105], v[82:85]
	v_mfma_f32_16x16x32_bf16 v[50:53], v[122:125], v[102:105], v[50:53]
	v_mfma_f32_16x16x32_bf16 v[70:73], v[110:113], v[106:109], v[70:73]
	ds_write_b128 v22, v[194:197] offset:30720
	v_mfma_f32_16x16x32_bf16 v[86:89], v[114:117], v[106:109], v[86:89]
	v_mfma_f32_16x16x32_bf16 v[90:93], v[118:121], v[106:109], v[90:93]
	v_mfma_f32_16x16x32_bf16 v[54:57], v[122:125], v[106:109], v[54:57]
	s_waitcnt lgkmcnt(0)
	s_barrier
	ds_read_b128 v[94:97], v39
	ds_read_b128 v[98:101], v39 offset:2560
	ds_read_b128 v[102:105], v39 offset:5120
	ds_read_b128 v[106:109], v39 offset:7680
	ds_read_b128 v[110:113], v40 offset:40960
	ds_read_b128 v[114:117], v40 offset:43520
	ds_read_b128 v[118:121], v40 offset:46080
	ds_read_b128 v[122:125], v40 offset:48640
	v_mfma_f32_16x16x32_bf16 v[126:129], v[222:225], v[206:209], v[126:129]
	v_mfma_f32_16x16x32_bf16 v[130:133], v[226:229], v[206:209], v[130:133]
	v_mfma_f32_16x16x32_bf16 v[134:137], v[230:233], v[206:209], v[134:137]
	v_mfma_f32_16x16x32_bf16 v[42:45], v[234:237], v[206:209], v[42:45]
	v_mfma_f32_16x16x32_bf16 v[58:61], v[222:225], v[210:213], v[58:61]
	v_mfma_f32_16x16x32_bf16 v[62:65], v[226:229], v[210:213], v[62:65]
	v_mfma_f32_16x16x32_bf16 v[74:77], v[230:233], v[210:213], v[74:77]
	v_mfma_f32_16x16x32_bf16 v[46:49], v[234:237], v[210:213], v[46:49]
	v_mfma_f32_16x16x32_bf16 v[66:69], v[222:225], v[214:217], v[66:69]
	v_mfma_f32_16x16x32_bf16 v[78:81], v[226:229], v[214:217], v[78:81]
	v_mfma_f32_16x16x32_bf16 v[82:85], v[230:233], v[214:217], v[82:85]
	v_mfma_f32_16x16x32_bf16 v[50:53], v[234:237], v[214:217], v[50:53]
	v_mfma_f32_16x16x32_bf16 v[70:73], v[222:225], v[218:221], v[70:73]
	v_mfma_f32_16x16x32_bf16 v[86:89], v[226:229], v[218:221], v[86:89]
	v_mfma_f32_16x16x32_bf16 v[90:93], v[230:233], v[218:221], v[90:93]
	v_mfma_f32_16x16x32_bf16 v[54:57], v[234:237], v[218:221], v[54:57]
	global_load_dwordx4 v[182:185], v[2:3], off offset:1536
	global_load_dwordx4 v[186:189], v[8:9], off offset:1536
	global_load_dwordx4 v[190:193], v[10:11], off offset:1536
	global_load_dwordx4 v[194:197], v[12:13], off offset:1536
	global_load_dwordx4 v[198:201], v[14:15], off offset:1536
	global_load_dwordx4 v[202:205], v[16:17], off offset:1536
	ds_read_b128 v[206:209], v30 offset:64
	ds_read_b128 v[210:213], v30 offset:2624
	ds_read_b128 v[214:217], v30 offset:5184
	ds_read_b128 v[218:221], v30 offset:7744
	ds_read_b128 v[222:225], v31 offset:41024
	ds_read_b128 v[226:229], v31 offset:43584
	ds_read_b128 v[230:233], v31 offset:46144
	ds_read_b128 v[234:237], v31 offset:48704
	s_waitcnt lgkmcnt(11)
;     ...
;   for (int k0 = 0; k0 < K; k0 += 128) {
;     G_READ(fa1, fb1, 0, 32);
;     if (k0 + 128 < K) G_LOAD(ra0, rb0, k0 + 128);
;     __builtin_amdgcn_sched_barrier(0);
;     G_MFMA_ST(fa0, fb0, ra1, rb1, 1);
;     __syncthreads();
;     G_READ(fa0, fb0, 1, 0);
;     __builtin_amdgcn_sched_barrier(0);
;     G_MFMA(fa1, fb1);
;     __builtin_amdgcn_sched_barrier(0);
;     G_READ(fa1, fb1, 1, 32);
;     if (k0 + 192 < K) G_LOAD(ra1, rb1, k0 + 192);
;     __builtin_amdgcn_sched_barrier(0);
;     if (k0 + 128 < K) {
;       G_MFMA_ST(fa0, fb0, ra0, rb0, 0);
;       __syncthreads();
;       G_READ(fa0, fb0, 0, 0);
;     } else {
;       G_MFMA(fa0, fb0);
;     }
;     __builtin_amdgcn_sched_barrier(0);
;     G_MFMA(fa1, fb1);
;     __builtin_amdgcn_sched_barrier(0);
;   }
	v_mfma_f32_16x16x32_bf16 v[126:129], v[110:113], v[94:97], v[126:129]
	s_waitcnt vmcnt(11)
	ds_write_b128 v22, v[138:141] offset:61440
	s_waitcnt vmcnt(7)
	ds_write_b128 v23, v[174:177] offset:61440
	s_waitcnt lgkmcnt(12)
	v_mfma_f32_16x16x32_bf16 v[130:133], v[114:117], v[94:97], v[130:133]
	s_waitcnt lgkmcnt(11)
	v_mfma_f32_16x16x32_bf16 v[134:137], v[118:121], v[94:97], v[134:137]
	s_waitcnt lgkmcnt(10)
	v_mfma_f32_16x16x32_bf16 v[42:45], v[122:125], v[94:97], v[42:45]
	v_mfma_f32_16x16x32_bf16 v[58:61], v[110:113], v[98:101], v[58:61]
	ds_write_b128 v24, v[142:145] offset:61440
	s_waitcnt vmcnt(6)
	ds_write_b128 v25, v[178:181] offset:61440
	v_mfma_f32_16x16x32_bf16 v[62:65], v[114:117], v[98:101], v[62:65]
	v_mfma_f32_16x16x32_bf16 v[74:77], v[118:121], v[98:101], v[74:77]
	v_mfma_f32_16x16x32_bf16 v[46:49], v[122:125], v[98:101], v[46:49]
	v_mfma_f32_16x16x32_bf16 v[66:69], v[110:113], v[102:105], v[66:69]
	ds_write_b128 v26, v[152:155] offset:61440
	v_mfma_f32_16x16x32_bf16 v[78:81], v[114:117], v[102:105], v[78:81]
	v_mfma_f32_16x16x32_bf16 v[82:85], v[118:121], v[102:105], v[82:85]
	v_mfma_f32_16x16x32_bf16 v[50:53], v[122:125], v[102:105], v[50:53]
	v_mfma_f32_16x16x32_bf16 v[70:73], v[110:113], v[106:109], v[70:73]
	ds_write_b128 v27, v[156:159] offset:61440
	v_mfma_f32_16x16x32_bf16 v[86:89], v[114:117], v[106:109], v[86:89]
	v_mfma_f32_16x16x32_bf16 v[90:93], v[118:121], v[106:109], v[90:93]
	v_mfma_f32_16x16x32_bf16 v[54:57], v[122:125], v[106:109], v[54:57]
	s_waitcnt lgkmcnt(0)
	s_barrier
	ds_read_b128 v[94:97], v39 offset:61440
	ds_read_b128 v[98:101], v39 offset:64000
	ds_read_b128 v[102:105], v32 offset:5120
	ds_read_b128 v[106:109], v32 offset:7680
	ds_read_b128 v[110:113], v33
	ds_read_b128 v[114:117], v33 offset:2560
	ds_read_b128 v[118:121], v33 offset:5120
	ds_read_b128 v[122:125], v33 offset:7680
	v_mfma_f32_16x16x32_bf16 v[126:129], v[222:225], v[206:209], v[126:129]
	v_mfma_f32_16x16x32_bf16 v[130:133], v[226:229], v[206:209], v[130:133]
	v_mfma_f32_16x16x32_bf16 v[134:137], v[230:233], v[206:209], v[134:137]
	v_mfma_f32_16x16x32_bf16 v[42:45], v[234:237], v[206:209], v[42:45]
	v_mfma_f32_16x16x32_bf16 v[58:61], v[222:225], v[210:213], v[58:61]
	v_mfma_f32_16x16x32_bf16 v[62:65], v[226:229], v[210:213], v[62:65]
	v_mfma_f32_16x16x32_bf16 v[74:77], v[230:233], v[210:213], v[74:77]
	v_mfma_f32_16x16x32_bf16 v[46:49], v[234:237], v[210:213], v[46:49]
	v_mfma_f32_16x16x32_bf16 v[66:69], v[222:225], v[214:217], v[66:69]
	v_mfma_f32_16x16x32_bf16 v[78:81], v[226:229], v[214:217], v[78:81]
	v_mfma_f32_16x16x32_bf16 v[82:85], v[230:233], v[214:217], v[82:85]
	v_mfma_f32_16x16x32_bf16 v[50:53], v[234:237], v[214:217], v[50:53]
	v_mfma_f32_16x16x32_bf16 v[70:73], v[222:225], v[218:221], v[70:73]
	v_mfma_f32_16x16x32_bf16 v[86:89], v[226:229], v[218:221], v[86:89]
	v_mfma_f32_16x16x32_bf16 v[90:93], v[230:233], v[218:221], v[90:93]
	v_mfma_f32_16x16x32_bf16 v[54:57], v[234:237], v[218:221], v[54:57]
	global_load_dwordx4 v[138:141], v[2:3], off offset:1664
	global_load_dwordx4 v[142:145], v[8:9], off offset:1664
	global_load_dwordx4 v[152:155], v[10:11], off offset:1664
	global_load_dwordx4 v[156:159], v[12:13], off offset:1664
	global_load_dwordx4 v[174:177], v[14:15], off offset:1664
	global_load_dwordx4 v[178:181], v[16:17], off offset:1664
	ds_read_b128 v[206:209], v30 offset:61504
	ds_read_b128 v[210:213], v30 offset:64064
	ds_read_b128 v[214:217], v34 offset:64
	ds_read_b128 v[218:221], v35 offset:64
	ds_read_b128 v[222:225], v41 offset:64
	ds_read_b128 v[226:229], v36 offset:64
	ds_read_b128 v[230:233], v37 offset:64
	ds_read_b128 v[234:237], v38 offset:64
	s_waitcnt lgkmcnt(11)
	v_mfma_f32_16x16x32_bf16 v[126:129], v[110:113], v[94:97], v[126:129]
	s_waitcnt vmcnt(11)
	ds_write_b128 v22, v[182:185]
	s_waitcnt vmcnt(7)
	ds_write_b128 v23, v[198:201]
	s_waitcnt lgkmcnt(12)
	v_mfma_f32_16x16x32_bf16 v[130:133], v[114:117], v[94:97], v[130:133]
	s_waitcnt lgkmcnt(11)
	v_mfma_f32_16x16x32_bf16 v[134:137], v[118:121], v[94:97], v[134:137]
	s_waitcnt lgkmcnt(10)
	v_mfma_f32_16x16x32_bf16 v[42:45], v[122:125], v[94:97], v[42:45]
	v_mfma_f32_16x16x32_bf16 v[58:61], v[110:113], v[98:101], v[58:61]
	ds_write_b128 v22, v[186:189] offset:10240
	s_waitcnt vmcnt(6)
	ds_write_b128 v25, v[202:205]
	v_mfma_f32_16x16x32_bf16 v[62:65], v[114:117], v[98:101], v[62:65]
	v_mfma_f32_16x16x32_bf16 v[74:77], v[118:121], v[98:101], v[74:77]
	v_mfma_f32_16x16x32_bf16 v[46:49], v[122:125], v[98:101], v[46:49]
	v_mfma_f32_16x16x32_bf16 v[66:69], v[110:113], v[102:105], v[66:69]
	ds_write_b128 v22, v[190:193] offset:20480
	v_mfma_f32_16x16x32_bf16 v[78:81], v[114:117], v[102:105], v[78:81]
	v_mfma_f32_16x16x32_bf16 v[82:85], v[118:121], v[102:105], v[82:85]
	v_mfma_f32_16x16x32_bf16 v[50:53], v[122:125], v[102:105], v[50:53]
	v_mfma_f32_16x16x32_bf16 v[70:73], v[110:113], v[106:109], v[70:73]
	ds_write_b128 v22, v[194:197] offset:30720
	v_mfma_f32_16x16x32_bf16 v[86:89], v[114:117], v[106:109], v[86:89]
	v_mfma_f32_16x16x32_bf16 v[90:93], v[118:121], v[106:109], v[90:93]
	v_mfma_f32_16x16x32_bf16 v[54:57], v[122:125], v[106:109], v[54:57]
	s_waitcnt lgkmcnt(0)
	s_barrier
;     ...
;   for (int k0 = 0; k0 < K; k0 += 128) {
;     G_READ(fa1, fb1, 0, 32);
;     if (k0 + 128 < K) G_LOAD(ra0, rb0, k0 + 128);
;     __builtin_amdgcn_sched_barrier(0);
;     G_MFMA_ST(fa0, fb0, ra1, rb1, 1);
;     __syncthreads();
;     G_READ(fa0, fb0, 1, 0);
;     __builtin_amdgcn_sched_barrier(0);
;     G_MFMA(fa1, fb1);
;     __builtin_amdgcn_sched_barrier(0);
;     G_READ(fa1, fb1, 1, 32);
;     if (k0 + 192 < K) G_LOAD(ra1, rb1, k0 + 192);
;     __builtin_amdgcn_sched_barrier(0);
;     if (k0 + 128 < K) {
;       G_MFMA_ST(fa0, fb0, ra0, rb0, 0);
;       __syncthreads();
;       G_READ(fa0, fb0, 0, 0);
;     } else {
;       G_MFMA(fa0, fb0);
;     }
;     __builtin_amdgcn_sched_barrier(0);
;     G_MFMA(fa1, fb1);
;     __builtin_amdgcn_sched_barrier(0);
;   }
	ds_read_b128 v[94:97], v39
	ds_read_b128 v[98:101], v39 offset:2560
	ds_read_b128 v[102:105], v39 offset:5120
	ds_read_b128 v[106:109], v39 offset:7680
	ds_read_b128 v[110:113], v40 offset:40960
	ds_read_b128 v[114:117], v40 offset:43520
	ds_read_b128 v[118:121], v40 offset:46080
	ds_read_b128 v[122:125], v40 offset:48640
	v_mfma_f32_16x16x32_bf16 v[126:129], v[222:225], v[206:209], v[126:129]
	v_mfma_f32_16x16x32_bf16 v[130:133], v[226:229], v[206:209], v[130:133]
	v_mfma_f32_16x16x32_bf16 v[134:137], v[230:233], v[206:209], v[134:137]
	v_mfma_f32_16x16x32_bf16 v[42:45], v[234:237], v[206:209], v[42:45]
	v_mfma_f32_16x16x32_bf16 v[58:61], v[222:225], v[210:213], v[58:61]
	v_mfma_f32_16x16x32_bf16 v[62:65], v[226:229], v[210:213], v[62:65]
	v_mfma_f32_16x16x32_bf16 v[74:77], v[230:233], v[210:213], v[74:77]
	v_mfma_f32_16x16x32_bf16 v[46:49], v[234:237], v[210:213], v[46:49]
	v_mfma_f32_16x16x32_bf16 v[66:69], v[222:225], v[214:217], v[66:69]
	v_mfma_f32_16x16x32_bf16 v[78:81], v[226:229], v[214:217], v[78:81]
	v_mfma_f32_16x16x32_bf16 v[82:85], v[230:233], v[214:217], v[82:85]
	v_mfma_f32_16x16x32_bf16 v[50:53], v[234:237], v[214:217], v[50:53]
	v_mfma_f32_16x16x32_bf16 v[70:73], v[222:225], v[218:221], v[70:73]
	v_mfma_f32_16x16x32_bf16 v[86:89], v[226:229], v[218:221], v[86:89]
	v_mfma_f32_16x16x32_bf16 v[90:93], v[230:233], v[218:221], v[90:93]
	v_mfma_f32_16x16x32_bf16 v[54:57], v[234:237], v[218:221], v[54:57]
	global_load_dwordx4 v[182:185], v[2:3], off offset:1792
	global_load_dwordx4 v[186:189], v[8:9], off offset:1792
	global_load_dwordx4 v[190:193], v[10:11], off offset:1792
	global_load_dwordx4 v[194:197], v[12:13], off offset:1792
	global_load_dwordx4 v[198:201], v[14:15], off offset:1792
	global_load_dwordx4 v[202:205], v[16:17], off offset:1792
	ds_read_b128 v[206:209], v30 offset:64
	ds_read_b128 v[210:213], v30 offset:2624
	ds_read_b128 v[214:217], v30 offset:5184
	ds_read_b128 v[218:221], v30 offset:7744
	ds_read_b128 v[222:225], v31 offset:41024
	ds_read_b128 v[226:229], v31 offset:43584
	ds_read_b128 v[230:233], v31 offset:46144
	ds_read_b128 v[234:237], v31 offset:48704
	s_waitcnt lgkmcnt(11)
	v_mfma_f32_16x16x32_bf16 v[126:129], v[110:113], v[94:97], v[126:129]
	s_waitcnt vmcnt(11)
	ds_write_b128 v22, v[138:141] offset:61440
	s_waitcnt vmcnt(7)
	ds_write_b128 v23, v[174:177] offset:61440
	s_waitcnt lgkmcnt(12)
	v_mfma_f32_16x16x32_bf16 v[130:133], v[114:117], v[94:97], v[130:133]
	s_waitcnt lgkmcnt(11)
	v_mfma_f32_16x16x32_bf16 v[134:137], v[118:121], v[94:97], v[134:137]
	s_waitcnt lgkmcnt(10)
	v_mfma_f32_16x16x32_bf16 v[42:45], v[122:125], v[94:97], v[42:45]
	v_mfma_f32_16x16x32_bf16 v[58:61], v[110:113], v[98:101], v[58:61]
	ds_write_b128 v24, v[142:145] offset:61440
	s_waitcnt vmcnt(6)
	ds_write_b128 v25, v[178:181] offset:61440
	v_mfma_f32_16x16x32_bf16 v[62:65], v[114:117], v[98:101], v[62:65]
	v_mfma_f32_16x16x32_bf16 v[74:77], v[118:121], v[98:101], v[74:77]
	v_mfma_f32_16x16x32_bf16 v[46:49], v[122:125], v[98:101], v[46:49]
	v_mfma_f32_16x16x32_bf16 v[66:69], v[110:113], v[102:105], v[66:69]
	ds_write_b128 v26, v[152:155] offset:61440
	v_mfma_f32_16x16x32_bf16 v[78:81], v[114:117], v[102:105], v[78:81]
	v_mfma_f32_16x16x32_bf16 v[82:85], v[118:121], v[102:105], v[82:85]
	v_mfma_f32_16x16x32_bf16 v[50:53], v[122:125], v[102:105], v[50:53]
	v_mfma_f32_16x16x32_bf16 v[70:73], v[110:113], v[106:109], v[70:73]
	ds_write_b128 v27, v[156:159] offset:61440
	v_mfma_f32_16x16x32_bf16 v[86:89], v[114:117], v[106:109], v[86:89]
	v_mfma_f32_16x16x32_bf16 v[90:93], v[118:121], v[106:109], v[90:93]
	v_mfma_f32_16x16x32_bf16 v[54:57], v[122:125], v[106:109], v[54:57]
	s_waitcnt lgkmcnt(0)
	s_barrier
	ds_read_b128 v[94:97], v39 offset:61440
	ds_read_b128 v[98:101], v39 offset:64000
	ds_read_b128 v[102:105], v32 offset:5120
	ds_read_b128 v[106:109], v32 offset:7680
	ds_read_b128 v[110:113], v33
	ds_read_b128 v[114:117], v33 offset:2560
	ds_read_b128 v[118:121], v33 offset:5120
	ds_read_b128 v[122:125], v33 offset:7680
	v_mfma_f32_16x16x32_bf16 v[126:129], v[222:225], v[206:209], v[126:129]
	v_mfma_f32_16x16x32_bf16 v[130:133], v[226:229], v[206:209], v[130:133]
	v_mfma_f32_16x16x32_bf16 v[134:137], v[230:233], v[206:209], v[134:137]
	v_mfma_f32_16x16x32_bf16 v[42:45], v[234:237], v[206:209], v[42:45]
	v_mfma_f32_16x16x32_bf16 v[58:61], v[222:225], v[210:213], v[58:61]
	v_mfma_f32_16x16x32_bf16 v[62:65], v[226:229], v[210:213], v[62:65]
	v_mfma_f32_16x16x32_bf16 v[74:77], v[230:233], v[210:213], v[74:77]
	v_mfma_f32_16x16x32_bf16 v[46:49], v[234:237], v[210:213], v[46:49]
	v_mfma_f32_16x16x32_bf16 v[66:69], v[222:225], v[214:217], v[66:69]
	v_mfma_f32_16x16x32_bf16 v[78:81], v[226:229], v[214:217], v[78:81]
	v_mfma_f32_16x16x32_bf16 v[82:85], v[230:233], v[214:217], v[82:85]
	v_mfma_f32_16x16x32_bf16 v[50:53], v[234:237], v[214:217], v[50:53]
	v_mfma_f32_16x16x32_bf16 v[70:73], v[222:225], v[218:221], v[70:73]
	v_mfma_f32_16x16x32_bf16 v[86:89], v[226:229], v[218:221], v[86:89]
	v_mfma_f32_16x16x32_bf16 v[90:93], v[230:233], v[218:221], v[90:93]
	v_mfma_f32_16x16x32_bf16 v[54:57], v[234:237], v[218:221], v[54:57]
	global_load_dwordx4 v[138:141], v[2:3], off offset:1920
	global_load_dwordx4 v[142:145], v[8:9], off offset:1920
	s_nop 0
	global_load_dwordx4 v[8:11], v[10:11], off offset:1920
	s_nop 0
	global_load_dwordx4 v[152:155], v[12:13], off offset:1920
	s_nop 0
	global_load_dwordx4 v[12:15], v[14:15], off offset:1920
	s_nop 0
	global_load_dwordx4 v[156:159], v[16:17], off offset:1920
	ds_read_b128 v[174:177], v30 offset:61504
	ds_read_b128 v[178:181], v30 offset:64064
	ds_read_b128 v[206:209], v34 offset:64
	ds_read_b128 v[210:213], v35 offset:64
	ds_read_b128 v[214:217], v41 offset:64
	ds_read_b128 v[218:221], v36 offset:64
	ds_read_b128 v[222:225], v37 offset:64
	ds_read_b128 v[226:229], v38 offset:64
	s_waitcnt lgkmcnt(11)
;     ...
;   for (int k0 = 0; k0 < K; k0 += 128) {
;     G_READ(fa1, fb1, 0, 32);
;     if (k0 + 128 < K) G_LOAD(ra0, rb0, k0 + 128);
;     __builtin_amdgcn_sched_barrier(0);
;     G_MFMA_ST(fa0, fb0, ra1, rb1, 1);
;     __syncthreads();
;     G_READ(fa0, fb0, 1, 0);
;     __builtin_amdgcn_sched_barrier(0);
;     G_MFMA(fa1, fb1);
;     __builtin_amdgcn_sched_barrier(0);
;     G_READ(fa1, fb1, 1, 32);
;     if (k0 + 192 < K) G_LOAD(ra1, rb1, k0 + 192);
;     __builtin_amdgcn_sched_barrier(0);
;     if (k0 + 128 < K) {
;       G_MFMA_ST(fa0, fb0, ra0, rb0, 0);
;       __syncthreads();
;       G_READ(fa0, fb0, 0, 0);
;     } else {
;       G_MFMA(fa0, fb0);
;     }
;     __builtin_amdgcn_sched_barrier(0);
;     G_MFMA(fa1, fb1);
;     __builtin_amdgcn_sched_barrier(0);
;   }
; __device__ __forceinline__ void phase_inproj(const Params& p, const int tidx) {
;     ...
;   for (int tile = blockIdx.x, rnd = 0; tile < 128 * NTN; tile += gridDim.x, rnd++) {
;     int mt = tile / NTN, nt = tile % NTN;
;     if (swz) {
;       int j = rnd * 32 + li;
;       int g = j / (4 * NTN), rem = j % (4 * NTN);
;       nt = rem >> 2;
;       mt = xcd * 16 + g * 4 + (rem & 3);
;     }
	v_mfma_f32_16x16x32_bf16 v[126:129], v[110:113], v[94:97], v[126:129]
	s_waitcnt vmcnt(11)
	ds_write_b128 v22, v[182:185]
	s_waitcnt vmcnt(7)
	ds_write_b128 v23, v[198:201]
	s_waitcnt lgkmcnt(12)
	v_mfma_f32_16x16x32_bf16 v[130:133], v[114:117], v[94:97], v[130:133]
	s_waitcnt lgkmcnt(11)
	v_mfma_f32_16x16x32_bf16 v[134:137], v[118:121], v[94:97], v[134:137]
	s_waitcnt lgkmcnt(10)
	v_mfma_f32_16x16x32_bf16 v[42:45], v[122:125], v[94:97], v[42:45]
	v_mfma_f32_16x16x32_bf16 v[58:61], v[110:113], v[98:101], v[58:61]
	ds_write_b128 v22, v[186:189] offset:10240
	s_waitcnt vmcnt(6)
	ds_write_b128 v25, v[202:205]
	v_mfma_f32_16x16x32_bf16 v[62:65], v[114:117], v[98:101], v[62:65]
	v_mfma_f32_16x16x32_bf16 v[74:77], v[118:121], v[98:101], v[74:77]
	v_mfma_f32_16x16x32_bf16 v[46:49], v[122:125], v[98:101], v[46:49]
	v_mfma_f32_16x16x32_bf16 v[66:69], v[110:113], v[102:105], v[66:69]
	ds_write_b128 v22, v[190:193] offset:20480
	v_mfma_f32_16x16x32_bf16 v[78:81], v[114:117], v[102:105], v[78:81]
	v_mfma_f32_16x16x32_bf16 v[82:85], v[118:121], v[102:105], v[82:85]
	v_mfma_f32_16x16x32_bf16 v[50:53], v[122:125], v[102:105], v[50:53]
	v_mfma_f32_16x16x32_bf16 v[70:73], v[110:113], v[106:109], v[70:73]
	ds_write_b128 v22, v[194:197] offset:30720
	v_mfma_f32_16x16x32_bf16 v[86:89], v[114:117], v[106:109], v[86:89]
	v_mfma_f32_16x16x32_bf16 v[90:93], v[118:121], v[106:109], v[90:93]
	v_mfma_f32_16x16x32_bf16 v[54:57], v[122:125], v[106:109], v[54:57]
	s_waitcnt lgkmcnt(0)
	s_barrier
	ds_read_b128 v[94:97], v39
	ds_read_b128 v[98:101], v39 offset:2560
	ds_read_b128 v[102:105], v39 offset:5120
	ds_read_b128 v[106:109], v39 offset:7680
	ds_read_b128 v[110:113], v40 offset:40960
	ds_read_b128 v[114:117], v40 offset:43520
	ds_read_b128 v[118:121], v40 offset:46080
	ds_read_b128 v[122:125], v40 offset:48640
	v_readlane_b32 s32, v251, 1
	s_add_i32 s32, s18, s32
	s_add_i32 s41, s0, 1
	s_cmpk_gt_i32 s32, 0x1cff
	s_cselect_b32 s32, s18, s32
	s_cselect_b32 s41, s0, s41
	v_readlane_b32 s42, v251, 12
	v_readlane_b32 s43, v251, 13
	s_and_b64 s[42:43], s[42:43], exec
	s_cbranch_scc0 .Lip_pf_lin
	s_lshl_b32 s42, s41, 5
	v_readlane_b32 s43, v251, 16
	s_add_i32 s42, s42, s43
	s_mul_hi_u32 s43, s42, 0x8d3dcb09
	s_lshr_b32 s43, s43, 7
	s_mul_i32 s98, s43, 0xe8
	s_sub_i32 s98, s42, s98
	s_lshl_b32 s43, s43, 2
	v_readlane_b32 s99, v251, 18
	s_lshr_b32 s42, s98, 2
	s_add_i32 s43, s43, s99
	s_and_b32 s98, s98, 3
	s_or_b32 s98, s43, s98
	s_branch .Lip_pf_go
.Lip_pf_lin:
	s_mul_hi_i32 s42, s32, 0x8d3dcb09
	s_add_i32 s42, s42, s32
	s_lshr_b32 s43, s42, 31
	s_ashr_i32 s42, s42, 5
	s_add_i32 s98, s42, s43
	s_mul_i32 s42, s98, 58
	s_sub_i32 s42, s32, s42
.Lip_pf_go:
	s_ashr_i32 s99, s98, 31
	s_lshl_b64 s[60:61], s[98:99], 19
	s_add_u32 s60, s50, s60
	s_addc_u32 s61, s51, s61
	s_ashr_i32 s43, s42, 31
	s_lshl_b64 s[62:63], s[42:43], 18
	v_readlane_b32 s98, v251, 20
	v_readlane_b32 s99, v251, 21
	s_add_u32 s62, s98, s62
	s_addc_u32 s63, s99, s63
	global_load_dword v151, v170, s[60:61]
	global_load_dword v151, v171, s[62:63]
	v_mfma_f32_16x16x32_bf16 v[126:129], v[214:217], v[174:177], v[126:129]
	v_mfma_f32_16x16x32_bf16 v[130:133], v[218:221], v[174:177], v[130:133]
	v_mfma_f32_16x16x32_bf16 v[134:137], v[222:225], v[174:177], v[134:137]
	v_mfma_f32_16x16x32_bf16 v[42:45], v[226:229], v[174:177], v[42:45]
	v_mfma_f32_16x16x32_bf16 v[58:61], v[214:217], v[178:181], v[58:61]
	v_mfma_f32_16x16x32_bf16 v[62:65], v[218:221], v[178:181], v[62:65]
	v_mfma_f32_16x16x32_bf16 v[74:77], v[222:225], v[178:181], v[74:77]
	v_mfma_f32_16x16x32_bf16 v[46:49], v[226:229], v[178:181], v[46:49]
	v_mfma_f32_16x16x32_bf16 v[66:69], v[214:217], v[206:209], v[66:69]
	v_mfma_f32_16x16x32_bf16 v[78:81], v[218:221], v[206:209], v[78:81]
	v_mfma_f32_16x16x32_bf16 v[82:85], v[222:225], v[206:209], v[82:85]
	v_mfma_f32_16x16x32_bf16 v[50:53], v[226:229], v[206:209], v[50:53]
	v_mfma_f32_16x16x32_bf16 v[70:73], v[214:217], v[210:213], v[70:73]
	v_mfma_f32_16x16x32_bf16 v[86:89], v[218:221], v[210:213], v[86:89]
	v_mfma_f32_16x16x32_bf16 v[90:93], v[222:225], v[210:213], v[90:93]
	v_mfma_f32_16x16x32_bf16 v[54:57], v[226:229], v[210:213], v[54:57]
	ds_read_b128 v[174:177], v30 offset:64
	ds_read_b128 v[178:181], v30 offset:2624
	ds_read_b128 v[182:185], v30 offset:5184
	ds_read_b128 v[186:189], v30 offset:7744
	ds_read_b128 v[190:193], v31 offset:41024
	ds_read_b128 v[194:197], v31 offset:43584
	ds_read_b128 v[198:201], v31 offset:46144
	ds_read_b128 v[202:205], v31 offset:48704
	s_waitcnt lgkmcnt(11)
	v_mfma_f32_16x16x32_bf16 v[126:129], v[110:113], v[94:97], v[126:129]
	s_waitcnt vmcnt(7)
	ds_write_b128 v22, v[138:141] offset:61440
	s_waitcnt vmcnt(3)
	ds_write_b128 v23, v[12:15] offset:61440
	s_waitcnt lgkmcnt(12)
	v_mfma_f32_16x16x32_bf16 v[130:133], v[114:117], v[94:97], v[130:133]
	s_waitcnt lgkmcnt(11)
	v_mfma_f32_16x16x32_bf16 v[134:137], v[118:121], v[94:97], v[134:137]
	s_waitcnt lgkmcnt(10)
	v_mfma_f32_16x16x32_bf16 v[12:15], v[122:125], v[94:97], v[42:45]
	v_mfma_f32_16x16x32_bf16 v[42:45], v[110:113], v[98:101], v[58:61]
	ds_write_b128 v24, v[142:145] offset:61440
	s_waitcnt vmcnt(2)
	ds_write_b128 v25, v[156:159] offset:61440
	v_mfma_f32_16x16x32_bf16 v[58:61], v[114:117], v[98:101], v[62:65]
	v_mfma_f32_16x16x32_bf16 v[62:65], v[118:121], v[98:101], v[74:77]
	v_mfma_f32_16x16x32_bf16 v[46:49], v[122:125], v[98:101], v[46:49]
	v_mfma_f32_16x16x32_bf16 v[66:69], v[110:113], v[102:105], v[66:69]
	ds_write_b128 v26, v[8:11] offset:61440
	v_mfma_f32_16x16x32_bf16 v[74:77], v[114:117], v[102:105], v[78:81]
	v_mfma_f32_16x16x32_bf16 v[78:81], v[118:121], v[102:105], v[82:85]
	v_mfma_f32_16x16x32_bf16 v[8:11], v[122:125], v[102:105], v[50:53]
	v_mfma_f32_16x16x32_bf16 v[50:53], v[110:113], v[106:109], v[70:73]
	ds_write_b128 v27, v[152:155] offset:61440
	v_mfma_f32_16x16x32_bf16 v[70:73], v[114:117], v[106:109], v[86:89]
	v_mfma_f32_16x16x32_bf16 v[82:85], v[118:121], v[106:109], v[90:93]
	v_mfma_f32_16x16x32_bf16 v[54:57], v[122:125], v[106:109], v[54:57]
	s_waitcnt lgkmcnt(0)
	s_barrier
;     ...
;     if (k0 + 128 < K) {
;       G_MFMA_ST(fa0, fb0, ra0, rb0, 0);
;       __syncthreads();
;       G_READ(fa0, fb0, 0, 0);
;     } else {
;       G_MFMA(fa0, fb0);
;     }
;     __builtin_amdgcn_sched_barrier(0);
;     G_MFMA(fa1, fb1);
;     __builtin_amdgcn_sched_barrier(0);
;   }
	ds_read_b128 v[86:89], v39 offset:61440
	ds_read_b128 v[90:93], v39 offset:64000
	ds_read_b128 v[94:97], v32 offset:5120
	ds_read_b128 v[98:101], v32 offset:7680
	ds_read_b128 v[102:105], v33
	ds_read_b128 v[106:109], v33 offset:2560
	ds_read_b128 v[110:113], v33 offset:5120
	ds_read_b128 v[114:117], v33 offset:7680
	v_mfma_f32_16x16x32_bf16 v[118:121], v[190:193], v[174:177], v[126:129]
	v_mfma_f32_16x16x32_bf16 v[122:125], v[194:197], v[174:177], v[130:133]
	v_mfma_f32_16x16x32_bf16 v[126:129], v[198:201], v[174:177], v[134:137]
	v_mfma_f32_16x16x32_bf16 v[12:15], v[202:205], v[174:177], v[12:15]
	v_mfma_f32_16x16x32_bf16 v[42:45], v[190:193], v[178:181], v[42:45]
	v_mfma_f32_16x16x32_bf16 v[58:61], v[194:197], v[178:181], v[58:61]
	v_mfma_f32_16x16x32_bf16 v[62:65], v[198:201], v[178:181], v[62:65]
	v_mfma_f32_16x16x32_bf16 v[46:49], v[202:205], v[178:181], v[46:49]
	v_mfma_f32_16x16x32_bf16 v[66:69], v[190:193], v[182:185], v[66:69]
	v_mfma_f32_16x16x32_bf16 v[74:77], v[194:197], v[182:185], v[74:77]
	v_mfma_f32_16x16x32_bf16 v[78:81], v[198:201], v[182:185], v[78:81]
	v_mfma_f32_16x16x32_bf16 v[8:11], v[202:205], v[182:185], v[8:11]
	v_mfma_f32_16x16x32_bf16 v[50:53], v[190:193], v[186:189], v[50:53]
	v_mfma_f32_16x16x32_bf16 v[70:73], v[194:197], v[186:189], v[70:73]
	v_mfma_f32_16x16x32_bf16 v[82:85], v[198:201], v[186:189], v[82:85]
	v_mfma_f32_16x16x32_bf16 v[54:57], v[202:205], v[186:189], v[54:57]
	ds_read_b128 v[130:133], v30 offset:61504
	ds_read_b128 v[134:137], v30 offset:64064
	ds_read_b128 v[138:141], v34 offset:64
	ds_read_b128 v[142:145], v35 offset:64
	ds_read_b128 v[152:155], v41 offset:64
	ds_read_b128 v[156:159], v36 offset:64
	ds_read_b128 v[174:177], v37 offset:64
	ds_read_b128 v[178:181], v38 offset:64
	s_waitcnt lgkmcnt(11)
	v_mfma_f32_16x16x32_bf16 v[118:121], v[102:105], v[86:89], v[118:121]
	s_waitcnt lgkmcnt(10)
	v_mfma_f32_16x16x32_bf16 v[122:125], v[106:109], v[86:89], v[122:125]
	s_waitcnt lgkmcnt(9)
	v_mfma_f32_16x16x32_bf16 v[126:129], v[110:113], v[86:89], v[126:129]
	s_waitcnt lgkmcnt(8)
	v_mfma_f32_16x16x32_bf16 v[12:15], v[114:117], v[86:89], v[12:15]
	v_mfma_f32_16x16x32_bf16 v[40:43], v[102:105], v[90:93], v[42:45]
	v_mfma_f32_16x16x32_bf16 v[58:61], v[106:109], v[90:93], v[58:61]
	v_mfma_f32_16x16x32_bf16 v[62:65], v[110:113], v[90:93], v[62:65]
	v_mfma_f32_16x16x32_bf16 v[44:47], v[114:117], v[90:93], v[46:49]
	v_mfma_f32_16x16x32_bf16 v[66:69], v[102:105], v[94:97], v[66:69]
	v_mfma_f32_16x16x32_bf16 v[74:77], v[106:109], v[94:97], v[74:77]
	v_mfma_f32_16x16x32_bf16 v[78:81], v[110:113], v[94:97], v[78:81]
	v_mfma_f32_16x16x32_bf16 v[8:11], v[114:117], v[94:97], v[8:11]
	v_mfma_f32_16x16x32_bf16 v[48:51], v[102:105], v[98:101], v[50:53]
	v_mfma_f32_16x16x32_bf16 v[70:73], v[106:109], v[98:101], v[70:73]
	v_mfma_f32_16x16x32_bf16 v[82:85], v[110:113], v[98:101], v[82:85]
	v_mfma_f32_16x16x32_bf16 v[52:55], v[114:117], v[98:101], v[54:57]
	s_waitcnt lgkmcnt(3)
	v_mfma_f32_16x16x32_bf16 v[86:89], v[152:155], v[130:133], v[118:121]
	s_waitcnt lgkmcnt(2)
	v_mfma_f32_16x16x32_bf16 v[90:93], v[156:159], v[130:133], v[122:125]
	s_waitcnt lgkmcnt(1)
	v_mfma_f32_16x16x32_bf16 v[94:97], v[174:177], v[130:133], v[126:129]
	s_waitcnt lgkmcnt(0)
; template <int TN, bool NTS = false>
; __device__ __forceinline__ void store_tile_bf16(const f32x4 (&acc)[4][TN], bf16_t* __restrict__ dst, int ldd, bf16_t* sT,
;                                                 const int tidx) {
;   constexpr int BN = 32 * TN, TS = BN + 8, CPR = BN / 8;
;   const int lane = tidx & 63, w = tidx >> 6;
;   const int wm = w >> 1, wn = w & 1, l15 = lane & 15, quad = lane >> 4;
;   __syncthreads();
; #pragma unroll
;   for (int i = 0; i < 4; i++)
; #pragma unroll
;     for (int j = 0; j < TN; j++)
; #pragma unroll
;       for (int r = 0; r < 4; r++)
;         sT[(wm * 64 + i * 16 + quad * 4 + r) * TS + wn * TN * 16 + j * 16 + l15] = f2bf(acc[i][j][r]);
;   __syncthreads();
; #pragma unroll
;   for (int c = tidx; c < 256 * CPR; c += NT) {
;     int row = c / CPR, cc = c % CPR;
;     const u32x4 v_ = *(const u32x4*)(sT + row * TS + cc * 8);
;     if (NTS) __builtin_nontemporal_store(v_, (u32x4*)(dst + (size_t)row * ldd + cc * 8));
;     else *(u32x4*)(dst + (size_t)row * ldd + cc * 8) = v_;
;   }
; __device__ __forceinline__ void phase_inproj(const Params& p, const int tidx) {
;     ...
;     store_tile_bf16<4, true>(acc, P + (size_t)mt * 256 * NP + nt * 128, NP, sA, tidx);
	v_mfma_f32_16x16x32_bf16 v[12:15], v[178:181], v[130:133], v[12:15]
	v_mfma_f32_16x16x32_bf16 v[40:43], v[152:155], v[134:137], v[40:43]
	v_mfma_f32_16x16x32_bf16 v[56:59], v[156:159], v[134:137], v[58:61]
	v_mfma_f32_16x16x32_bf16 v[60:63], v[174:177], v[134:137], v[62:65]
	v_mfma_f32_16x16x32_bf16 v[44:47], v[178:181], v[134:137], v[44:47]
	v_mfma_f32_16x16x32_bf16 v[64:67], v[152:155], v[138:141], v[66:69]
	v_mfma_f32_16x16x32_bf16 v[74:77], v[156:159], v[138:141], v[74:77]
	v_mfma_f32_16x16x32_bf16 v[78:81], v[174:177], v[138:141], v[78:81]
	v_mfma_f32_16x16x32_bf16 v[8:11], v[178:181], v[138:141], v[8:11]
	v_mfma_f32_16x16x32_bf16 v[48:51], v[152:155], v[142:145], v[48:51]
	v_mfma_f32_16x16x32_bf16 v[68:71], v[156:159], v[142:145], v[70:73]
	v_mfma_f32_16x16x32_bf16 v[82:85], v[174:177], v[142:145], v[82:85]
	v_mfma_f32_16x16x32_bf16 v[52:55], v[178:181], v[142:145], v[52:55]
	s_mul_hi_i32 s13, s14, 0x3a0000
	s_mul_i32 s14, s14, 0x3a0000
	s_add_u32 s14, s94, s14
	s_addc_u32 s15, s95, s13
	s_lshl_b32 s12, s12, 8
	s_add_u32 s12, s14, s12
	s_addc_u32 s13, s15, 0
	v_lshrrev_b32_e32 v2, 7, v150
	v_and_b32_e32 v3, 7, v150
	v_lshl_or_b32 v2, v2, 6, v3
	v_mul_u32_u24_e32 v2, 0x3a00, v2
	v_bfe_u32 v3, v150, 6, 1
	v_bfe_u32 v16, v150, 3, 1
	v_lshl_or_b32 v3, v3, 1, v16
	v_bfe_u32 v16, v150, 4, 2
	v_lshl_or_b32 v3, v3, 2, v16
	v_lshl_add_u32 v2, v3, 4, v2
	v_add_u32_e32 v3, 0x1d000, v2
	v_cvt_pk_bf16_f32 v86, v86, v87
	v_cvt_pk_bf16_f32 v87, v88, v89
	v_cvt_pk_bf16_f32 v88, v90, v91
	v_cvt_pk_bf16_f32 v89, v92, v93
	v_cvt_pk_bf16_f32 v94, v94, v95
	v_cvt_pk_bf16_f32 v95, v96, v97
	v_cvt_pk_bf16_f32 v96, v12, v13
	v_cvt_pk_bf16_f32 v97, v14, v15
	v_mov_b32_e32 v90, v86
	v_mov_b32_e32 v91, v87
	v_mov_b32_e32 v92, v88
	v_mov_b32_e32 v93, v89
	v_mov_b32_dpp v86, v94 row_ror:8 row_mask:0xf bank_mask:0xc
	v_mov_b32_dpp v87, v95 row_ror:8 row_mask:0xf bank_mask:0xc
	v_mov_b32_dpp v88, v96 row_ror:8 row_mask:0xf bank_mask:0xc
	v_mov_b32_dpp v89, v97 row_ror:8 row_mask:0xf bank_mask:0xc
	v_mov_b32_dpp v94, v90 row_ror:8 row_mask:0xf bank_mask:0x3
	v_mov_b32_dpp v95, v91 row_ror:8 row_mask:0xf bank_mask:0x3
	v_mov_b32_dpp v96, v92 row_ror:8 row_mask:0xf bank_mask:0x3
	v_mov_b32_dpp v97, v93 row_ror:8 row_mask:0xf bank_mask:0x3
	global_store_dwordx4 v2, v[86:89], s[12:13] nt
	global_store_dwordx4 v3, v[94:97], s[12:13] nt
	s_add_u32 s12, s12, 0x3a000
	s_addc_u32 s13, s13, 0
	v_cvt_pk_bf16_f32 v40, v40, v41
	v_cvt_pk_bf16_f32 v41, v42, v43
	v_cvt_pk_bf16_f32 v42, v56, v57
	v_cvt_pk_bf16_f32 v43, v58, v59
	v_cvt_pk_bf16_f32 v60, v60, v61
	v_cvt_pk_bf16_f32 v61, v62, v63
	v_cvt_pk_bf16_f32 v62, v44, v45
	v_cvt_pk_bf16_f32 v63, v46, v47
	v_mov_b32_e32 v56, v40
	v_mov_b32_e32 v57, v41
	v_mov_b32_e32 v58, v42
	v_mov_b32_e32 v59, v43
	v_mov_b32_dpp v40, v60 row_ror:8 row_mask:0xf bank_mask:0xc
	v_mov_b32_dpp v41, v61 row_ror:8 row_mask:0xf bank_mask:0xc
	v_mov_b32_dpp v42, v62 row_ror:8 row_mask:0xf bank_mask:0xc
	v_mov_b32_dpp v43, v63 row_ror:8 row_mask:0xf bank_mask:0xc
	v_mov_b32_dpp v60, v56 row_ror:8 row_mask:0xf bank_mask:0x3
	v_mov_b32_dpp v61, v57 row_ror:8 row_mask:0xf bank_mask:0x3
	v_mov_b32_dpp v62, v58 row_ror:8 row_mask:0xf bank_mask:0x3
	v_mov_b32_dpp v63, v59 row_ror:8 row_mask:0xf bank_mask:0x3
	global_store_dwordx4 v2, v[40:43], s[12:13] nt
	global_store_dwordx4 v3, v[60:63], s[12:13] nt
	s_add_u32 s12, s12, 0x3a000
	s_addc_u32 s13, s13, 0
	v_cvt_pk_bf16_f32 v64, v64, v65
	v_cvt_pk_bf16_f32 v65, v66, v67
	v_cvt_pk_bf16_f32 v66, v74, v75
	v_cvt_pk_bf16_f32 v67, v76, v77
	v_cvt_pk_bf16_f32 v78, v78, v79
	v_cvt_pk_bf16_f32 v79, v80, v81
	v_cvt_pk_bf16_f32 v80, v8, v9
	v_cvt_pk_bf16_f32 v81, v10, v11
	v_mov_b32_e32 v74, v64
	v_mov_b32_e32 v75, v65
	v_mov_b32_e32 v76, v66
	v_mov_b32_e32 v77, v67
	v_mov_b32_dpp v64, v78 row_ror:8 row_mask:0xf bank_mask:0xc
	v_mov_b32_dpp v65, v79 row_ror:8 row_mask:0xf bank_mask:0xc
	v_mov_b32_dpp v66, v80 row_ror:8 row_mask:0xf bank_mask:0xc
	v_mov_b32_dpp v67, v81 row_ror:8 row_mask:0xf bank_mask:0xc
	v_mov_b32_dpp v78, v74 row_ror:8 row_mask:0xf bank_mask:0x3
	v_mov_b32_dpp v79, v75 row_ror:8 row_mask:0xf bank_mask:0x3
	v_mov_b32_dpp v80, v76 row_ror:8 row_mask:0xf bank_mask:0x3
	v_mov_b32_dpp v81, v77 row_ror:8 row_mask:0xf bank_mask:0x3
	global_store_dwordx4 v2, v[64:67], s[12:13] nt
	global_store_dwordx4 v3, v[78:81], s[12:13] nt
	s_add_u32 s12, s12, 0x3a000
	s_addc_u32 s13, s13, 0
	v_cvt_pk_bf16_f32 v48, v48, v49
	v_cvt_pk_bf16_f32 v49, v50, v51
	v_cvt_pk_bf16_f32 v50, v68, v69
	v_cvt_pk_bf16_f32 v51, v70, v71
	v_cvt_pk_bf16_f32 v82, v82, v83
	v_cvt_pk_bf16_f32 v83, v84, v85
	v_cvt_pk_bf16_f32 v84, v52, v53
	v_cvt_pk_bf16_f32 v85, v54, v55
	v_mov_b32_e32 v68, v48
	v_mov_b32_e32 v69, v49
	v_mov_b32_e32 v70, v50
	v_mov_b32_e32 v71, v51
	v_mov_b32_dpp v48, v82 row_ror:8 row_mask:0xf bank_mask:0xc
	v_mov_b32_dpp v49, v83 row_ror:8 row_mask:0xf bank_mask:0xc
	v_mov_b32_dpp v50, v84 row_ror:8 row_mask:0xf bank_mask:0xc
	v_mov_b32_dpp v51, v85 row_ror:8 row_mask:0xf bank_mask:0xc
	v_mov_b32_dpp v82, v68 row_ror:8 row_mask:0xf bank_mask:0x3
	v_mov_b32_dpp v83, v69 row_ror:8 row_mask:0xf bank_mask:0x3
	v_mov_b32_dpp v84, v70 row_ror:8 row_mask:0xf bank_mask:0x3
	v_mov_b32_dpp v85, v71 row_ror:8 row_mask:0xf bank_mask:0x3
	global_store_dwordx4 v2, v[48:51], s[12:13] nt
	global_store_dwordx4 v3, v[82:85], s[12:13] nt
	s_branch .LBB0_581
